# retention out_unit: the four V-tile loads issued together instead of behind three successive waits
# baseline (speedup 1.0000x reference)
; DI float logsig(float x) { return -log1pf(__expf(-x)); }
; DI void out_unit(const Inputs& in, int l, unsigned char* ws, int half, int u, LAS unsigned char* lds, int tid) {
;     ...
;     const int L = half ? 2048 : 4096, NC = L / 128, h = u & 3, sn = u >> 2, s = sn / NC, n = sn % NC, row0 = s * L + n * 128, pos0 = n * 128;
;     bf16_t* proj = (bf16_t*)(ws + WS_PROJ); const float* rtc = (const float*)(ws + WS_RTC); const float* rts = (const float*)(ws + WS_RTS);
;     const bf16_t* SS = (const bf16_t*)(ws + WS_KV + 32 * MiB);
;     const float lgf = logsig(in.ret_decay[l * 8 + h]), lgb = logsig(in.ret_decay[l * 8 + 4 + h]);
.LBB0_731:
	s_ashr_i32 s13, s26, 2
	s_abs_i32 s15, s13
	s_mul_hi_u32 s16, s15, s24
	s_mul_i32 s17, s16, s20
	s_sub_i32 s15, s15, s17
	s_and_b32 s27, s26, 3
	s_ashr_i32 s14, s26, 31
	s_add_i32 s17, s16, 1
	s_sub_i32 s28, s15, s20
	s_cmp_ge_u32 s15, s20
	s_cselect_b32 s16, s17, s16
	s_cselect_b32 s15, s28, s15
	s_add_i32 s17, s16, 1
	s_cmp_ge_u32 s15, s20
	s_cselect_b32 s15, s17, s16
	s_xor_b32 s15, s15, s14
	s_sub_i32 s14, s15, s14
	s_mul_i32 s15, s14, s20
	s_sub_i32 s13, s13, s15
	s_lshl_b32 s14, s14, s21
	s_lshl_b32 s13, s13, 7
	s_or_b32 s44, s27, s77
	s_add_i32 s14, s13, s14
	s_lshl_b64 s[16:17], s[44:45], 2
	s_waitcnt lgkmcnt(0)
	s_add_u32 s16, s4, s16
	v_mov_b32_e32 v66, v64
	s_addc_u32 s17, s5, s17
	global_load_dword v0, v177, s[16:17]
	v_ashrrev_i32_e32 v19, 6, v66
	s_movk_i32 s15, 0x1100
	v_lshlrev_b32_e32 v91, 3, v66
	v_and_b32_e32 v20, 56, v91
	v_lshlrev_b32_e32 v176, 1, v20
	v_or_b32_e32 v21, 64, v91
	v_and_b32_e32 v68, 15, v66
	v_and_b32_e32 v18, 63, v66
	v_or_b32_e32 v141, 16, v68
	v_or_b32_e32 v114, 32, v68
	v_or_b32_e32 v95, 48, v18
	v_or_b32_e32 v112, 64, v68
	v_or_b32_e32 v110, 0x50, v68
	v_or_b32_e32 v108, 0x60, v68
	v_or_b32_e32 v100, 0x70, v18
	v_mul_u32_u24_e32 v96, 0x88, v95
	v_mad_u32_u24 v97, v68, s1, v224
	v_mad_u32_u24 v98, v68, s1, v254
	v_mad_u32_u24 v99, v68, s1, v219
	v_mul_u32_u24_e32 v101, 0x88, v100
	s_waitcnt vmcnt(0)
	v_mul_f32_e32 v0, 0xbfb8aa3b, v0
	v_exp_f32_e32 v2, v0
	s_nop 0
	v_add_f32_e32 v3, 1.0, v2
	v_add_f32_e32 v0, -1.0, v3
	v_sub_f32_e32 v1, v0, v3
	v_add_f32_e32 v1, 1.0, v1
	v_sub_f32_e32 v0, v2, v0
	v_add_f32_e32 v4, v0, v1
	v_frexp_mant_f32_e32 v0, v3
	v_cmp_gt_f32_e32 vcc, s31, v0
	v_cvt_f64_f32_e32 v[0:1], v3
	v_frexp_exp_i32_f64_e32 v0, v[0:1]
	v_subbrev_co_u32_e32 v0, vcc, 0, v0, vcc
	v_sub_u32_e32 v1, 0, v0
	v_ldexp_f32 v3, v3, v1
	v_ldexp_f32 v1, v4, v1
	v_add_f32_e32 v4, -1.0, v3
	v_add_f32_e32 v5, 1.0, v4
	v_sub_f32_e32 v5, v3, v5
	v_add_f32_e32 v5, v1, v5
	v_add_f32_e32 v6, v4, v5
	v_sub_f32_e32 v4, v6, v4
	v_sub_f32_e32 v4, v5, v4
	v_add_f32_e32 v5, 1.0, v3
	v_add_f32_e32 v7, -1.0, v5
	v_sub_f32_e32 v3, v3, v7
	v_add_f32_e32 v1, v1, v3
	v_add_f32_e32 v3, v5, v1
	v_sub_f32_e32 v5, v3, v5
	v_sub_f32_e32 v1, v1, v5
	v_rcp_f32_e32 v5, v3
	v_cvt_f32_i32_e32 v0, v0
	v_cmp_neq_f32_e32 vcc, s34, v2
	v_mul_f32_e32 v7, v6, v5
	v_mul_f32_e32 v8, v3, v7
	v_fma_f32 v9, v7, v3, -v8
	v_fmac_f32_e32 v9, v7, v1
	v_add_f32_e32 v10, v8, v9
	v_sub_f32_e32 v11, v6, v10
	v_sub_f32_e32 v6, v6, v11
	v_sub_f32_e32 v8, v10, v8
	v_sub_f32_e32 v6, v6, v10
	v_add_f32_e32 v4, v4, v6
	v_sub_f32_e32 v6, v8, v9
	v_add_f32_e32 v4, v6, v4
	v_add_f32_e32 v6, v11, v4
	v_mul_f32_e32 v8, v5, v6
	v_mul_f32_e32 v9, v3, v8
	v_fma_f32 v3, v8, v3, -v9
	v_fmac_f32_e32 v3, v8, v1
	v_sub_f32_e32 v1, v11, v6
	v_add_f32_e32 v1, v4, v1
	v_add_f32_e32 v4, v9, v3
	v_sub_f32_e32 v10, v6, v4
	v_sub_f32_e32 v6, v6, v10
	v_sub_f32_e32 v9, v4, v9
	v_sub_f32_e32 v4, v6, v4
	v_add_f32_e32 v1, v1, v4
	v_sub_f32_e32 v3, v9, v3
	v_add_f32_e32 v1, v3, v1
	v_add_f32_e32 v3, v7, v8
	v_add_f32_e32 v1, v10, v1
	v_sub_f32_e32 v4, v3, v7
	v_mul_f32_e32 v1, v5, v1
	v_sub_f32_e32 v4, v8, v4
	v_add_f32_e32 v1, v4, v1
	v_mul_f32_e32 v7, 0x3f317218, v0
	v_add_f32_e32 v4, v3, v1
	v_fma_f32 v8, v0, s33, -v7
	v_mul_f32_e32 v5, v4, v4
	v_fmac_f32_e32 v8, 0xb102e308, v0
	v_sub_f32_e32 v0, v4, v3
	v_fmamk_f32 v6, v5, 0x3e9b6dac, v218
	v_sub_f32_e32 v0, v1, v0
	v_add_f32_e32 v1, v7, v8
	v_fmaak_f32 v6, v5, v6, 0x3f2aaada
	v_sub_f32_e32 v3, v1, v7
	v_ldexp_f32 v7, v4, 1
	v_mul_f32_e32 v4, v4, v5
	v_mul_f32_e32 v4, v4, v6
	v_add_f32_e32 v5, v7, v4
	v_sub_f32_e32 v6, v5, v7
	v_ldexp_f32 v0, v0, 1
	v_sub_f32_e32 v4, v4, v6
	v_add_f32_e32 v0, v0, v4
	v_add_f32_e32 v4, v5, v0
	v_sub_f32_e32 v5, v4, v5
	v_sub_f32_e32 v0, v0, v5
	v_add_f32_e32 v5, v1, v4
	v_sub_f32_e32 v6, v5, v1
	v_sub_f32_e32 v7, v5, v6
	v_sub_f32_e32 v3, v8, v3
	v_sub_f32_e32 v1, v1, v7
	v_sub_f32_e32 v4, v4, v6
	v_add_f32_e32 v1, v4, v1
	v_add_f32_e32 v4, v3, v0
	v_sub_f32_e32 v6, v4, v3
	v_sub_f32_e32 v7, v4, v6
	v_sub_f32_e32 v3, v3, v7
	v_sub_f32_e32 v0, v0, v6
	v_add_f32_e32 v1, v4, v1
	v_add_f32_e32 v0, v0, v3
	v_add_f32_e32 v3, v5, v1
	v_sub_f32_e32 v4, v3, v5
	v_sub_f32_e32 v1, v1, v4
	v_add_f32_e32 v0, v0, v1
	v_add_f32_e32 v0, v3, v0
	v_cndmask_b32_e32 v0, v221, v0, vcc
	v_cmp_ngt_f32_e32 vcc, -1.0, v2
	s_nop 1
	v_cndmask_b32_e32 v0, v222, v0, vcc
	v_cmp_neq_f32_e32 vcc, -1.0, v2
	s_nop 1
	v_cndmask_b32_e32 v0, v223, v0, vcc
	v_cmp_lt_f32_e64 vcc, |v2|, s35
	s_nop 1
	v_cndmask_b32_e32 v60, v0, v2, vcc
	global_load_dword v0, v177, s[16:17] offset:16
	s_waitcnt vmcnt(0)
; #define LAS __attribute__((address_space(3)))
; DI float logsig(float x) { return -log1pf(__expf(-x)); }
; DI void out_unit(const Inputs& in, int l, unsigned char* ws, int half, int u, LAS unsigned char* lds, int tid) {
;     ...
;     const float lgf = logsig(in.ret_decay[l * 8 + h]), lgb = logsig(in.ret_decay[l * 8 + 4 + h]);
;     const int wave = tid >> 6, lane = tid & 63, l15 = lane & 15, quad = lane >> 4;
;     LAS unsigned char* Qt = lds; LAS unsigned char* Kt = lds + TILE_B; LAS unsigned char* VTt = lds + 2 * TILE_B; LAS unsigned char* Ps = lds + 3 * TILE_B + wave * (16 * TS * 2);
;     stage_rot_rm_b(Qt, proj + (size_t)row0 * PC + C_RQ + 128 * h, rtc, rts, pos0, 1.0f, tid);
	v_mul_f32_e32 v0, 0xbfb8aa3b, v0
	v_exp_f32_e32 v2, v0
	s_nop 0
	v_add_f32_e32 v3, 1.0, v2
	v_add_f32_e32 v0, -1.0, v3
	v_sub_f32_e32 v1, v0, v3
	v_add_f32_e32 v1, 1.0, v1
	v_sub_f32_e32 v0, v2, v0
	v_add_f32_e32 v4, v0, v1
	v_frexp_mant_f32_e32 v0, v3
	v_cmp_gt_f32_e32 vcc, s31, v0
	v_cvt_f64_f32_e32 v[0:1], v3
	v_frexp_exp_i32_f64_e32 v0, v[0:1]
	v_subbrev_co_u32_e32 v0, vcc, 0, v0, vcc
	v_sub_u32_e32 v1, 0, v0
	v_ldexp_f32 v3, v3, v1
	v_ldexp_f32 v1, v4, v1
	v_add_f32_e32 v4, -1.0, v3
	v_add_f32_e32 v5, 1.0, v4
	v_sub_f32_e32 v5, v3, v5
	v_add_f32_e32 v5, v1, v5
	v_add_f32_e32 v6, v4, v5
	v_sub_f32_e32 v4, v6, v4
	v_sub_f32_e32 v4, v5, v4
	v_add_f32_e32 v5, 1.0, v3
	v_add_f32_e32 v7, -1.0, v5
	v_sub_f32_e32 v3, v3, v7
	v_add_f32_e32 v1, v1, v3
	v_add_f32_e32 v3, v5, v1
	v_sub_f32_e32 v5, v3, v5
	v_sub_f32_e32 v1, v1, v5
	v_rcp_f32_e32 v5, v3
	v_cvt_f32_i32_e32 v0, v0
	v_cmp_neq_f32_e32 vcc, s34, v2
	v_mul_f32_e32 v7, v6, v5
	v_mul_f32_e32 v8, v3, v7
	v_fma_f32 v9, v7, v3, -v8
	v_fmac_f32_e32 v9, v7, v1
	v_add_f32_e32 v10, v8, v9
	v_sub_f32_e32 v11, v6, v10
	v_sub_f32_e32 v6, v6, v11
	v_sub_f32_e32 v8, v10, v8
	v_sub_f32_e32 v6, v6, v10
	v_add_f32_e32 v4, v4, v6
	v_sub_f32_e32 v6, v8, v9
	v_add_f32_e32 v4, v6, v4
	v_add_f32_e32 v6, v11, v4
	v_mul_f32_e32 v8, v5, v6
	v_mul_f32_e32 v9, v3, v8
	v_fma_f32 v3, v8, v3, -v9
	v_fmac_f32_e32 v3, v8, v1
	v_sub_f32_e32 v1, v11, v6
	v_add_f32_e32 v1, v4, v1
	v_add_f32_e32 v4, v9, v3
	v_sub_f32_e32 v10, v6, v4
	v_sub_f32_e32 v6, v6, v10
	v_sub_f32_e32 v9, v4, v9
	v_sub_f32_e32 v4, v6, v4
	v_add_f32_e32 v1, v1, v4
	v_sub_f32_e32 v3, v9, v3
	v_add_f32_e32 v1, v3, v1
	v_add_f32_e32 v3, v7, v8
	v_add_f32_e32 v1, v10, v1
	v_sub_f32_e32 v4, v3, v7
	v_mul_f32_e32 v1, v5, v1
	v_sub_f32_e32 v4, v8, v4
	v_add_f32_e32 v1, v4, v1
	v_mul_f32_e32 v7, 0x3f317218, v0
	v_add_f32_e32 v4, v3, v1
	v_fma_f32 v8, v0, s33, -v7
	v_mul_f32_e32 v5, v4, v4
	v_fmac_f32_e32 v8, 0xb102e308, v0
	v_sub_f32_e32 v0, v4, v3
	v_fmamk_f32 v6, v5, 0x3e9b6dac, v218
	v_sub_f32_e32 v0, v1, v0
	v_add_f32_e32 v1, v7, v8
	v_fmaak_f32 v6, v5, v6, 0x3f2aaada
	v_sub_f32_e32 v3, v1, v7
	v_ldexp_f32 v7, v4, 1
	v_mul_f32_e32 v4, v4, v5
	v_mul_f32_e32 v4, v4, v6
	v_add_f32_e32 v5, v7, v4
	v_sub_f32_e32 v6, v5, v7
	v_ldexp_f32 v0, v0, 1
	v_sub_f32_e32 v4, v4, v6
	v_add_f32_e32 v0, v0, v4
	v_add_f32_e32 v4, v5, v0
	v_sub_f32_e32 v5, v4, v5
	v_sub_f32_e32 v0, v0, v5
	v_add_f32_e32 v5, v1, v4
	v_sub_f32_e32 v6, v5, v1
	v_sub_f32_e32 v7, v5, v6
	v_sub_f32_e32 v3, v8, v3
	v_sub_f32_e32 v1, v1, v7
	v_sub_f32_e32 v4, v4, v6
	v_add_f32_e32 v1, v4, v1
	v_add_f32_e32 v4, v3, v0
	v_sub_f32_e32 v6, v4, v3
	v_sub_f32_e32 v7, v4, v6
	v_sub_f32_e32 v3, v3, v7
	v_sub_f32_e32 v0, v0, v6
	v_add_f32_e32 v1, v4, v1
	v_add_f32_e32 v0, v0, v3
	v_add_f32_e32 v3, v5, v1
	v_sub_f32_e32 v4, v3, v5
	v_sub_f32_e32 v1, v1, v4
	v_add_f32_e32 v0, v0, v1
	v_add_f32_e32 v0, v3, v0
	v_cndmask_b32_e32 v0, v221, v0, vcc
	v_cmp_ngt_f32_e32 vcc, -1.0, v2
	v_ashrrev_i32_e32 v10, 3, v66
	v_ashrrev_i32_e32 v11, 31, v10
	v_cndmask_b32_e32 v0, v222, v0, vcc
	v_cmp_neq_f32_e32 vcc, -1.0, v2
	v_add_u32_e32 v12, s13, v10
	v_lshlrev_b64 v[8:9], 14, v[10:11]
	v_cndmask_b32_e32 v0, v223, v0, vcc
	v_cmp_lt_f32_e64 vcc, |v2|, s35
	v_ashrrev_i32_e32 v13, 31, v12
	v_lshlrev_b64 v[14:15], 8, v[12:13]
	v_cndmask_b32_e32 v67, v0, v2, vcc
	v_mul_lo_u32 v0, v19, s15
	s_ashr_i32 s15, s14, 31
	s_lshl_b64 s[16:17], s[14:15], 14
	s_add_u32 s15, s6, s16
	s_addc_u32 s17, s7, s17
	s_lshl_b32 s44, s27, 8
	s_add_u32 s16, s15, s44
	s_addc_u32 s17, s17, 0
	v_add_u32_e32 v65, s42, v0
	v_lshl_add_u64 v[0:1], s[16:17], 0, v[8:9]
	v_lshl_add_u64 v[0:1], v[0:1], 0, v[176:177]
	v_lshl_add_u64 v[16:17], s[8:9], 0, v[14:15]
	v_lshlrev_b32_e32 v12, 2, v20
	v_mov_b32_e32 v13, v177
	v_lshl_add_u64 v[14:15], s[10:11], 0, v[14:15]
	global_load_dwordx4 v[4:7], v[0:1], off offset:3072
	s_nop 0
	global_load_dwordx4 v[0:3], v[0:1], off offset:3200
	v_lshl_add_u64 v[22:23], v[16:17], 0, v[12:13]
	v_lshl_add_u64 v[30:31], v[14:15], 0, v[12:13]
	global_load_dwordx4 v[14:17], v[22:23], off offset:16
	s_nop 0
	global_load_dwordx4 v[22:25], v[22:23], off
	s_nop 0
	global_load_dwordx4 v[26:29], v[30:31], off offset:16
	s_nop 0
	global_load_dwordx4 v[30:33], v[30:31], off
	v_add_u32_e32 v58, 64, v10
	v_ashrrev_i32_e32 v59, 31, v58
	v_add_u32_e32 v42, s13, v58
	v_lshlrev_b64 v[62:63], 14, v[58:59]
	v_ashrrev_i32_e32 v43, 31, v42
	v_lshl_add_u64 v[34:35], s[16:17], 0, v[62:63]
	v_lshlrev_b64 v[42:43], 8, v[42:43]
	v_lshl_add_u64 v[38:39], v[34:35], 0, v[176:177]
	v_lshl_add_u64 v[44:45], s[8:9], 0, v[42:43]
	global_load_dwordx4 v[34:37], v[38:39], off offset:3072
	s_nop 0
	global_load_dwordx4 v[38:41], v[38:39], off offset:3200
	v_lshl_add_u64 v[46:47], v[44:45], 0, v[12:13]
	v_lshl_add_u64 v[42:43], s[10:11], 0, v[42:43]
	v_lshl_add_u64 v[12:13], v[42:43], 0, v[12:13]
	global_load_dwordx4 v[42:45], v[46:47], off offset:16
	s_nop 0
	global_load_dwordx4 v[46:49], v[46:47], off
	s_nop 0
	global_load_dwordx4 v[50:53], v[12:13], off offset:16
	global_load_dwordx4 v[54:57], v[12:13], off
	v_mul_lo_u32 v59, v10, s1
	v_and_b32_e32 v11, 0x78, v10
	v_xad_u32 v11, v11, v20, v59
	v_lshl_add_u32 v61, v11, 1, 0
	s_add_u32 s28, s16, 0x1000
	s_addc_u32 s29, s17, 0
	s_movk_i32 s13, 0x60
	s_waitcnt vmcnt(11)
	v_lshlrev_b32_e32 v12, 16, v4
	s_waitcnt vmcnt(10)
	v_lshlrev_b32_e32 v70, 16, v0
	v_and_b32_e32 v71, 0xffff0000, v0
	v_and_b32_e32 v13, 0xffff0000, v4
	s_waitcnt vmcnt(6)
; #define LAS __attribute__((address_space(3)))
; DI unsigned cvt_pk_bf16(float lo, float hi) { const f32x2 v = {lo, hi}; return __builtin_bit_cast(unsigned, __builtin_convertvector(v, bf16x2_t)); }
; DI void unpack8(const u32x4 w, float (&f)[8]) { f[0] = bflo(w.x); f[1] = bfhi(w.x); f[2] = bflo(w.y); f[3] = bfhi(w.y); f[4] = bflo(w.z); f[5] = bfhi(w.z); f[6] = bflo(w.w); f[7] = bfhi(w.w); }
; DI void rot_apply(const RotIn& r, float (&o1)[8], float (&o2)[8]) {
;     float x1[8], x2[8]; unpack8(r.a, x1); unpack8(r.b, x2);
; #pragma unroll
;     for (int e = 0; e < 8; ++e) { const float c = e < 4 ? r.ca[e & 3] : r.cb[e & 3], s = e < 4 ? r.sa[e & 3] : r.sb[e & 3]; o1[e] = x1[e] * c - x2[e] * s; o2[e] = x1[e] * s + x2[e] * c; }
; }
; DI void stage_rot_rm_b(LAS unsigned char* dst, const bf16_t* src, const float* rtc, const float* rts, int pos0, float scale, int tid) {
;     const RotIn r0 = rot_load(src, rtc, rts, pos0, tid >> 3, (tid & 7) * 8), r1 = rot_load(src, rtc, rts, pos0, 64 + (tid >> 3), (tid & 7) * 8);
; #pragma unroll
;     for (int k = 0; k < 2; ++k) { const int j = 64 * k + (tid >> 3), d0 = (tid & 7) * 8; float o1[8], o2[8]; rot_apply(k ? r1 : r0, o1, o2);
;         u32x4 w1, w2; w1.x = cvt_pk_bf16(o1[0] * scale, o1[1] * scale); w1.y = cvt_pk_bf16(o1[2] * scale, o1[3] * scale); w1.z = cvt_pk_bf16(o1[4] * scale, o1[5] * scale); w1.w = cvt_pk_bf16(o1[6] * scale, o1[7] * scale);
;         w2.x = cvt_pk_bf16(o2[0] * scale, o2[1] * scale); w2.y = cvt_pk_bf16(o2[2] * scale, o2[3] * scale); w2.z = cvt_pk_bf16(o2[4] * scale, o2[5] * scale); w2.w = cvt_pk_bf16(o2[6] * scale, o2[7] * scale);
;         *(LAS u32x4*)(dst + sw(j, d0) * 2) = w1; *(LAS u32x4*)(dst + sw(j, 64 + d0) * 2) = w2; }
	v_pk_mul_f32 v[72:73], v[30:31], v[70:71]
	v_lshlrev_b32_e32 v0, 16, v1
	v_pk_fma_f32 v[72:73], v[22:23], v[12:13], v[72:73] neg_lo:[0,0,1] neg_hi:[0,0,1]
	v_pk_mul_f32 v[12:13], v[30:31], v[12:13]
	v_and_b32_e32 v1, 0xffff0000, v1
	v_pk_fma_f32 v[12:13], v[22:23], v[70:71], v[12:13]
	v_lshlrev_b32_e32 v4, 16, v5
	v_and_b32_e32 v5, 0xffff0000, v5
	v_pk_mul_f32 v[70:71], v[32:33], v[0:1]
	s_nop 0
	v_pk_fma_f32 v[70:71], v[24:25], v[4:5], v[70:71] neg_lo:[0,0,1] neg_hi:[0,0,1]
	v_pk_mul_f32 v[4:5], v[32:33], v[4:5]
	s_nop 0
	v_pk_fma_f32 v[74:75], v[24:25], v[0:1], v[4:5]
	v_lshlrev_b32_e32 v4, 16, v2
	v_and_b32_e32 v5, 0xffff0000, v2
	v_lshlrev_b32_e32 v0, 16, v6
	v_and_b32_e32 v1, 0xffff0000, v6
	v_pk_mul_f32 v[76:77], v[26:27], v[4:5]
	v_lshlrev_b32_e32 v2, 16, v3
	v_pk_fma_f32 v[76:77], v[14:15], v[0:1], v[76:77] neg_lo:[0,0,1] neg_hi:[0,0,1]
	v_pk_mul_f32 v[0:1], v[26:27], v[0:1]
	v_and_b32_e32 v3, 0xffff0000, v3
	v_pk_fma_f32 v[78:79], v[14:15], v[4:5], v[0:1]
	v_lshlrev_b32_e32 v0, 16, v7
	v_and_b32_e32 v1, 0xffff0000, v7
	v_pk_mul_f32 v[4:5], v[28:29], v[2:3]
	v_cvt_pk_bf16_f32 v6, v78, v79
	v_pk_fma_f32 v[4:5], v[16:17], v[0:1], v[4:5] neg_lo:[0,0,1] neg_hi:[0,0,1]
	v_pk_mul_f32 v[0:1], v[28:29], v[0:1]
	s_nop 0
	v_pk_fma_f32 v[80:81], v[16:17], v[2:3], v[0:1]
	v_cvt_pk_bf16_f32 v0, v72, v73
	v_cvt_pk_bf16_f32 v1, v70, v71
	v_cvt_pk_bf16_f32 v2, v76, v77
	v_cvt_pk_bf16_f32 v3, v4, v5
	ds_write_b128 v61, v[0:3]
	v_bitop3_b32 v0, v21, s0, v10 bitop3:0x48
	v_add_u32_e32 v0, v0, v59
	v_cvt_pk_bf16_f32 v4, v12, v13
	v_cvt_pk_bf16_f32 v5, v74, v75
	v_cvt_pk_bf16_f32 v7, v80, v81
	v_lshl_add_u32 v69, v0, 1, 0
	s_waitcnt vmcnt(4)
	v_lshlrev_b32_e32 v2, 16, v38
	v_and_b32_e32 v3, 0xffff0000, v38
	ds_write_b128 v69, v[4:7]
	v_lshlrev_b32_e32 v0, 16, v34
	v_and_b32_e32 v1, 0xffff0000, v34
	s_waitcnt vmcnt(0)
	v_pk_mul_f32 v[4:5], v[54:55], v[2:3]
	s_nop 0
	v_pk_fma_f32 v[4:5], v[46:47], v[0:1], v[4:5] neg_lo:[0,0,1] neg_hi:[0,0,1]
	v_pk_mul_f32 v[0:1], v[54:55], v[0:1]
	s_nop 0
	v_pk_fma_f32 v[6:7], v[46:47], v[2:3], v[0:1]
	v_lshlrev_b32_e32 v2, 16, v39
	v_and_b32_e32 v3, 0xffff0000, v39
	v_lshlrev_b32_e32 v0, 16, v35
	v_and_b32_e32 v1, 0xffff0000, v35
	v_pk_mul_f32 v[10:11], v[56:57], v[2:3]
	s_nop 0
	v_pk_fma_f32 v[10:11], v[48:49], v[0:1], v[10:11] neg_lo:[0,0,1] neg_hi:[0,0,1]
	v_pk_mul_f32 v[0:1], v[56:57], v[0:1]
	s_nop 0
	v_pk_fma_f32 v[12:13], v[48:49], v[2:3], v[0:1]
	v_lshlrev_b32_e32 v2, 16, v40
	v_and_b32_e32 v3, 0xffff0000, v40
	v_lshlrev_b32_e32 v0, 16, v36
	v_and_b32_e32 v1, 0xffff0000, v36
	v_pk_mul_f32 v[34:35], v[50:51], v[2:3]
	s_nop 0
	v_pk_fma_f32 v[34:35], v[42:43], v[0:1], v[34:35] neg_lo:[0,0,1] neg_hi:[0,0,1]
	v_pk_mul_f32 v[0:1], v[50:51], v[0:1]
	s_nop 0
	v_pk_fma_f32 v[38:39], v[42:43], v[2:3], v[0:1]
	v_lshlrev_b32_e32 v2, 16, v41
	v_and_b32_e32 v3, 0xffff0000, v41
	v_lshlrev_b32_e32 v0, 16, v37
	v_and_b32_e32 v1, 0xffff0000, v37
	v_pk_mul_f32 v[36:37], v[52:53], v[2:3]
	s_nop 0
	v_pk_fma_f32 v[36:37], v[44:45], v[0:1], v[36:37] neg_lo:[0,0,1] neg_hi:[0,0,1]
	v_pk_mul_f32 v[0:1], v[52:53], v[0:1]
	s_nop 0
	v_pk_fma_f32 v[40:41], v[44:45], v[2:3], v[0:1]
	v_cvt_pk_bf16_f32 v1, v10, v11
	v_add_u32_e32 v10, 0x2200, v59
	v_and_b32_e32 v11, 0x78, v58
	v_xad_u32 v11, v11, v20, v10
	v_cvt_pk_bf16_f32 v0, v4, v5
	v_cvt_pk_bf16_f32 v2, v34, v35
	v_cvt_pk_bf16_f32 v3, v36, v37
	v_cvt_pk_bf16_f32 v4, v6, v7
	v_cvt_pk_bf16_f32 v7, v40, v41
	v_lshl_add_u32 v40, v11, 1, 0
	ds_write_b128 v40, v[0:3]
	v_bitop3_b32 v0, v58, s0, v21 bitop3:0x48
	v_add_u32_e32 v0, v0, v10
	v_cvt_pk_bf16_f32 v5, v12, v13
	v_cvt_pk_bf16_f32 v6, v38, v39
	v_lshl_add_u32 v41, v0, 1, 0
	v_lshl_add_u64 v[0:1], s[28:29], 0, v[8:9]
	ds_write_b128 v41, v[4:7]
	v_lshl_add_u64 v[4:5], v[0:1], 0, v[176:177]
	global_load_dwordx4 v[0:3], v[4:5], off
	s_nop 0
	global_load_dwordx4 v[4:7], v[4:5], off offset:128
	v_lshl_add_u64 v[8:9], s[28:29], 0, v[62:63]
	v_lshl_add_u64 v[12:13], v[8:9], 0, v[176:177]
	global_load_dwordx4 v[8:11], v[12:13], off
	global_load_dwordx4 v[34:37], v[12:13], off offset:128
	v_ashrrev_i32_e32 v58, 4, v66
	v_ashrrev_i32_e32 v59, 31, v58
	v_bitop3_b32 v134, v58, s0, v91 bitop3:0x48
	s_waitcnt vmcnt(3)
	v_lshlrev_b32_e32 v12, 16, v0
	s_waitcnt vmcnt(2)
	v_lshlrev_b32_e32 v20, 16, v4
	v_and_b32_e32 v21, 0xffff0000, v4
	v_and_b32_e32 v13, 0xffff0000, v0
	v_pk_mul_f32 v[38:39], v[22:23], v[20:21]
	v_pk_mul_f32 v[20:21], v[30:31], v[20:21]
	v_pk_fma_f32 v[38:39], v[30:31], v[12:13], v[38:39]
	v_pk_fma_f32 v[12:13], v[22:23], v[12:13], v[20:21] neg_lo:[0,0,1] neg_hi:[0,0,1]
	v_lshlrev_b32_e32 v20, 16, v5
	v_pk_mul_f32 v[12:13], v[12:13], s[76:77] op_sel_hi:[1,0]
	v_and_b32_e32 v21, 0xffff0000, v5
	v_cvt_pk_bf16_f32 v0, v12, v13
	v_pk_mul_f32 v[12:13], v[38:39], s[76:77] op_sel_hi:[1,0]
	v_pk_mul_f32 v[22:23], v[24:25], v[20:21]
	v_cvt_pk_bf16_f32 v4, v12, v13
	v_lshlrev_b32_e32 v12, 16, v1
	v_and_b32_e32 v13, 0xffff0000, v1
	v_pk_mul_f32 v[20:21], v[32:33], v[20:21]
	v_pk_fma_f32 v[22:23], v[32:33], v[12:13], v[22:23]
	v_pk_fma_f32 v[12:13], v[24:25], v[12:13], v[20:21] neg_lo:[0,0,1] neg_hi:[0,0,1]
	v_lshlrev_b32_e32 v20, 16, v6
	v_pk_mul_f32 v[12:13], v[12:13], s[76:77] op_sel_hi:[1,0]
	v_and_b32_e32 v21, 0xffff0000, v6
	v_cvt_pk_bf16_f32 v1, v12, v13
	v_pk_mul_f32 v[12:13], v[22:23], s[76:77] op_sel_hi:[1,0]
	v_pk_mul_f32 v[22:23], v[14:15], v[20:21]
	v_cvt_pk_bf16_f32 v5, v12, v13
	v_lshlrev_b32_e32 v12, 16, v2
	v_and_b32_e32 v13, 0xffff0000, v2
	v_pk_mul_f32 v[20:21], v[26:27], v[20:21]
	v_pk_fma_f32 v[22:23], v[26:27], v[12:13], v[22:23]
	v_pk_fma_f32 v[12:13], v[14:15], v[12:13], v[20:21] neg_lo:[0,0,1] neg_hi:[0,0,1]
	v_lshlrev_b32_e32 v14, 16, v7
	v_pk_mul_f32 v[12:13], v[12:13], s[76:77] op_sel_hi:[1,0]
	v_and_b32_e32 v15, 0xffff0000, v7
	v_cvt_pk_bf16_f32 v2, v12, v13
	v_pk_mul_f32 v[12:13], v[22:23], s[76:77] op_sel_hi:[1,0]
	v_pk_mul_f32 v[20:21], v[16:17], v[14:15]
	v_cvt_pk_bf16_f32 v6, v12, v13
	v_lshlrev_b32_e32 v12, 16, v3
	v_and_b32_e32 v13, 0xffff0000, v3
	v_pk_mul_f32 v[14:15], v[28:29], v[14:15]
	v_pk_fma_f32 v[20:21], v[28:29], v[12:13], v[20:21]
	v_pk_fma_f32 v[12:13], v[16:17], v[12:13], v[14:15] neg_lo:[0,0,1] neg_hi:[0,0,1]
	v_mul_u32_u24_e32 v17, 0x88, v68
	v_pk_mul_f32 v[12:13], v[12:13], s[76:77] op_sel_hi:[1,0]
	s_nop 0
	v_cvt_pk_bf16_f32 v3, v12, v13
	v_pk_mul_f32 v[12:13], v[20:21], s[76:77] op_sel_hi:[1,0]
	v_mad_u32_u24 v20, v68, s1, v225
	v_cvt_pk_bf16_f32 v7, v12, v13
	ds_write_b128 v61, v[0:3] offset:34816
	ds_write_b128 v69, v[4:7] offset:34816
	s_waitcnt vmcnt(0)
; #define LAS __attribute__((address_space(3)))
; DI unsigned cvt_pk_bf16(float lo, float hi) { const f32x2 v = {lo, hi}; return __builtin_bit_cast(unsigned, __builtin_convertvector(v, bf16x2_t)); }
; DI void stage_rot_rm_b(LAS unsigned char* dst, const bf16_t* src, const float* rtc, const float* rts, int pos0, float scale, int tid) {
;     ...
;     for (int k = 0; k < 2; ++k) { const int j = 64 * k + (tid >> 3), d0 = (tid & 7) * 8; float o1[8], o2[8]; rot_apply(k ? r1 : r0, o1, o2);
;         u32x4 w1, w2; w1.x = cvt_pk_bf16(o1[0] * scale, o1[1] * scale); w1.y = cvt_pk_bf16(o1[2] * scale, o1[3] * scale); w1.z = cvt_pk_bf16(o1[4] * scale, o1[5] * scale); w1.w = cvt_pk_bf16(o1[6] * scale, o1[7] * scale);
;         w2.x = cvt_pk_bf16(o2[0] * scale, o2[1] * scale); w2.y = cvt_pk_bf16(o2[2] * scale, o2[3] * scale); w2.z = cvt_pk_bf16(o2[4] * scale, o2[5] * scale); w2.w = cvt_pk_bf16(o2[6] * scale, o2[7] * scale);
;         *(LAS u32x4*)(dst + sw(j, d0) * 2) = w1; *(LAS u32x4*)(dst + sw(j, 64 + d0) * 2) = w2; }
; DI void stage_T_b(LAS unsigned char* dst, const bf16_t* src, int tid) {
;     LAS bf16_t* T = (LAS bf16_t*)dst;
;     u32x4 wv[4];
; #pragma unroll
;     for (int k = 0; k < 4; ++k) { const int it = tid + 512 * k, j = it >> 4, c0 = (it & 15) * 8; wv[k] = *(const u32x4*)(src + (size_t)j * PC + c0); }
; #pragma unroll
;     for (int k = 0; k < 4; ++k) { const int it = tid + 512 * k, j = it >> 4, c0 = (it & 15) * 8; const u32x4 w = wv[k];
;         T[sw(c0 + 0, j)] = (bf16_t)(w.x & 0xffff); T[sw(c0 + 1, j)] = (bf16_t)(w.x >> 16); T[sw(c0 + 2, j)] = (bf16_t)(w.y & 0xffff); T[sw(c0 + 3, j)] = (bf16_t)(w.y >> 16);
;         T[sw(c0 + 4, j)] = (bf16_t)(w.z & 0xffff); T[sw(c0 + 5, j)] = (bf16_t)(w.z >> 16); T[sw(c0 + 6, j)] = (bf16_t)(w.w & 0xffff); T[sw(c0 + 7, j)] = (bf16_t)(w.w >> 16); }
; }
	v_lshlrev_b32_e32 v2, 16, v34
	v_and_b32_e32 v3, 0xffff0000, v34
	v_lshlrev_b32_e32 v0, 16, v8
	v_and_b32_e32 v1, 0xffff0000, v8
	v_pk_mul_f32 v[4:5], v[46:47], v[2:3]
	v_pk_mul_f32 v[2:3], v[54:55], v[2:3]
	v_pk_fma_f32 v[4:5], v[54:55], v[0:1], v[4:5]
	v_pk_fma_f32 v[0:1], v[46:47], v[0:1], v[2:3] neg_lo:[0,0,1] neg_hi:[0,0,1]
	v_pk_mul_f32 v[2:3], v[4:5], s[76:77] op_sel_hi:[1,0]
	v_lshlrev_b32_e32 v6, 16, v35
	v_and_b32_e32 v7, 0xffff0000, v35
	v_cvt_pk_bf16_f32 v4, v2, v3
	v_lshlrev_b32_e32 v2, 16, v9
	v_and_b32_e32 v3, 0xffff0000, v9
	v_pk_mul_f32 v[8:9], v[48:49], v[6:7]
	v_pk_mul_f32 v[6:7], v[56:57], v[6:7]
	v_pk_fma_f32 v[8:9], v[56:57], v[2:3], v[8:9]
	v_pk_fma_f32 v[2:3], v[48:49], v[2:3], v[6:7] neg_lo:[0,0,1] neg_hi:[0,0,1]
	v_pk_mul_f32 v[0:1], v[0:1], s[76:77] op_sel_hi:[1,0]
	v_pk_mul_f32 v[2:3], v[2:3], s[76:77] op_sel_hi:[1,0]
	v_cvt_pk_bf16_f32 v0, v0, v1
	v_cvt_pk_bf16_f32 v1, v2, v3
	v_pk_mul_f32 v[2:3], v[8:9], s[76:77] op_sel_hi:[1,0]
	v_lshlrev_b32_e32 v6, 16, v36
	v_and_b32_e32 v7, 0xffff0000, v36
	v_cvt_pk_bf16_f32 v5, v2, v3
	v_lshlrev_b32_e32 v2, 16, v10
	v_and_b32_e32 v3, 0xffff0000, v10
	v_pk_mul_f32 v[8:9], v[42:43], v[6:7]
	v_pk_mul_f32 v[6:7], v[50:51], v[6:7]
	v_pk_fma_f32 v[8:9], v[50:51], v[2:3], v[8:9]
	v_pk_fma_f32 v[2:3], v[42:43], v[2:3], v[6:7] neg_lo:[0,0,1] neg_hi:[0,0,1]
	v_pk_mul_f32 v[6:7], v[8:9], s[76:77] op_sel_hi:[1,0]
	v_lshlrev_b32_e32 v8, 16, v11
	v_and_b32_e32 v9, 0xffff0000, v11
	v_lshlrev_b32_e32 v10, 16, v37
	v_and_b32_e32 v11, 0xffff0000, v37
	v_pk_mul_f32 v[12:13], v[44:45], v[10:11]
	v_pk_mul_f32 v[10:11], v[52:53], v[10:11]
	v_pk_fma_f32 v[12:13], v[52:53], v[8:9], v[12:13]
	v_pk_fma_f32 v[8:9], v[44:45], v[8:9], v[10:11] neg_lo:[0,0,1] neg_hi:[0,0,1]
	v_pk_mul_f32 v[2:3], v[2:3], s[76:77] op_sel_hi:[1,0]
	v_pk_mul_f32 v[8:9], v[8:9], s[76:77] op_sel_hi:[1,0]
	v_cvt_pk_bf16_f32 v2, v2, v3
	v_cvt_pk_bf16_f32 v3, v8, v9
	v_pk_mul_f32 v[8:9], v[12:13], s[76:77] op_sel_hi:[1,0]
	v_cvt_pk_bf16_f32 v6, v6, v7
	v_cvt_pk_bf16_f32 v7, v8, v9
	v_and_b32_e32 v8, 0x78, v91
	v_lshlrev_b32_e32 v176, 1, v8
	ds_write_b128 v40, v[0:3] offset:34816
	ds_write_b128 v41, v[4:7] offset:34816
	v_lshl_add_u64 v[0:1], s[16:17], 0, v[176:177]
	v_lshl_add_u64 v[4:5], v[0:1], 0, s[36:37]
	v_lshlrev_b64 v[0:1], 14, v[58:59]
	v_lshl_add_u64 v[6:7], v[4:5], 0, v[0:1]
	v_add_u32_e32 v0, 0x200, v66
	v_ashrrev_i32_e32 v56, 4, v0
	v_ashrrev_i32_e32 v57, 31, v56
	v_lshlrev_b64 v[0:1], 14, v[56:57]
	v_lshl_add_u64 v[2:3], v[4:5], 0, v[0:1]
	v_add_u32_e32 v0, 0x400, v66
	v_add_u32_e32 v9, 0x600, v66
	v_ashrrev_i32_e32 v54, 4, v0
	v_ashrrev_i32_e32 v52, 4, v9
	v_ashrrev_i32_e32 v55, 31, v54
	v_ashrrev_i32_e32 v53, 31, v52
	v_lshlrev_b64 v[0:1], 14, v[54:55]
	v_lshlrev_b64 v[10:11], 14, v[52:53]
	v_mov_b32_e32 v9, s82
	v_lshl_add_u64 v[0:1], v[4:5], 0, v[0:1]
	v_lshl_add_u64 v[4:5], v[4:5], 0, v[10:11]
	v_mad_u32_u24 v10, v8, s38, v9
	v_lshlrev_b32_e32 v9, 1, v58
	v_lshlrev_b32_e32 v8, 1, v134
	v_and_b32_e32 v9, 14, v9
	v_add3_u32 v11, v10, v8, v9
	global_load_dwordx4 v[150:153], v[6:7], off
	global_load_dwordx4 v[154:157], v[2:3], off
	global_load_dwordx4 v[158:161], v[0:1], off
	global_load_dwordx4 v[162:165], v[4:5], off
	s_waitcnt vmcnt(0)
	v_mov_b32_e32 v6, v150
	v_mov_b32_e32 v7, v151
	v_mov_b32_e32 v8, v152
	v_mov_b32_e32 v9, v153
	ds_write_b16 v11, v6
	ds_write_b16_d16_hi v11, v6 offset:272
	ds_write_b16 v11, v7 offset:544
	ds_write_b16_d16_hi v11, v7 offset:816
	ds_write_b16 v11, v8 offset:1088
	ds_write_b16_d16_hi v11, v8 offset:1360
	ds_write_b16 v11, v9 offset:1632
	ds_write_b16_d16_hi v11, v9 offset:1904
	v_bitop3_b32 v135, v56, s0, v91 bitop3:0x48
	v_lshlrev_b32_e32 v7, 1, v56
	v_lshlrev_b32_e32 v6, 1, v135
	v_and_b32_e32 v7, 14, v7
	v_add3_u32 v11, v10, v6, v7
	s_nop 0
	v_mov_b32_e32 v6, v154
	v_mov_b32_e32 v7, v155
	v_mov_b32_e32 v8, v156
	v_mov_b32_e32 v9, v157
	ds_write_b16 v11, v6
	ds_write_b16_d16_hi v11, v6 offset:272
	ds_write_b16 v11, v7 offset:544
	ds_write_b16_d16_hi v11, v7 offset:816
	ds_write_b16 v11, v8 offset:1088
	ds_write_b16_d16_hi v11, v8 offset:1360
	ds_write_b16 v11, v9 offset:1632
	s_nop 0
	ds_write_b16_d16_hi v11, v9 offset:1904
	v_bitop3_b32 v136, v54, s0, v91 bitop3:0x48
	v_lshlrev_b32_e32 v9, 1, v54
	v_lshlrev_b32_e32 v8, 1, v136
	v_and_b32_e32 v9, 14, v9
	v_add3_u32 v8, v10, v8, v9
	s_nop 0
	v_mov_b32_e32 v0, v158
	v_mov_b32_e32 v1, v159
	v_mov_b32_e32 v2, v160
	v_mov_b32_e32 v3, v161
	ds_write_b16 v8, v0
	ds_write_b16_d16_hi v8, v0 offset:272
	ds_write_b16 v8, v1 offset:544
	ds_write_b16_d16_hi v8, v1 offset:816
	ds_write_b16 v8, v2 offset:1088
	ds_write_b16_d16_hi v8, v2 offset:1360
	ds_write_b16 v8, v3 offset:1632
	ds_write_b16_d16_hi v8, v3 offset:1904
	v_bitop3_b32 v133, v52, s0, v91 bitop3:0x48
	v_lshlrev_b32_e32 v1, 1, v52
	v_lshlrev_b32_e32 v0, 1, v133
	v_and_b32_e32 v1, 14, v1
	v_add3_u32 v0, v10, v0, v1
	v_lshlrev_b32_e32 v69, 4, v19
	s_nop 0
	v_mov_b32_e32 v4, v162
	v_mov_b32_e32 v5, v163
	v_mov_b32_e32 v6, v164
	v_mov_b32_e32 v7, v165
	ds_write_b16 v0, v4
	ds_write_b16_d16_hi v0, v4 offset:272
	ds_write_b16 v0, v5 offset:544
	ds_write_b16_d16_hi v0, v5 offset:816
	ds_write_b16 v0, v6 offset:1088
	ds_write_b16_d16_hi v0, v6 offset:1360
	ds_write_b16 v0, v7 offset:1632
	ds_write_b16_d16_hi v0, v7 offset:1904
	v_or_b32_e32 v0, v69, v68
	v_lshrrev_b32_e32 v8, 1, v66
	v_and_b32_e32 v16, 24, v8
	v_mul_lo_u32 v50, v0, s1
	v_bitop3_b32 v51, v69, s0, v68 bitop3:0xc8
	v_xad_u32 v0, v51, v16, v50
	v_lshl_add_u32 v53, v0, 1, 0
	s_waitcnt lgkmcnt(0)
	s_barrier
; #define LAS __attribute__((address_space(3)))
; DI void mma16(f32x4 (&acc)[8], const LAS unsigned char* At, int arow0, const LAS unsigned char* Bt, int lane) {
;     const int l15 = lane & 15, quad = lane >> 4;
; #pragma unroll
;     for (int ks = 0; ks < 4; ++ks) {
;         const bf16x8 a = *(const LAS bf16x8*)(At + sw(arow0 + l15, 32 * ks + 8 * quad) * 2);
; #pragma unroll
;         for (int cg = 0; cg < 8; ++cg) { const bf16x8 b = *(const LAS bf16x8*)(Bt + sw(16 * cg + l15, 32 * ks + 8 * quad) * 2);
;             acc[cg] = __builtin_amdgcn_mfma_f32_16x16x32_bf16(a, b, acc[cg], 0, 0, 0); }
;     }
; }
	v_and_b32_e32 v19, 8, v66
	ds_read_b128 v[0:3], v53
	v_bitop3_b32 v4, v8, v19, 24 bitop3:0x6c
	v_bitop3_b32 v8, v141, v8, 24 bitop3:0x28
	v_mad_u32_u24 v21, v68, s1, v220
	v_bitop3_b32 v12, v114, v16, 40 bitop3:0x6c
	v_bitop3_b32 v22, v95, v16, 56 bitop3:0x6c
	v_bitop3_b32 v26, v112, v16, s39 bitop3:0x6c
	v_bitop3_b32 v30, v110, v16, s40 bitop3:0x6c
	v_bitop3_b32 v34, v108, v16, s41 bitop3:0x6c
	v_bitop3_b32 v18, v100, v16, s0 bitop3:0x6c
	v_add_lshl_u32 v104, v4, v17, 1
	v_add_lshl_u32 v105, v8, v20, 1
	v_add_lshl_u32 v106, v12, v21, 1
	v_add_lshl_u32 v107, v22, v96, 1
	v_add_lshl_u32 v109, v26, v97, 1
	v_add_lshl_u32 v111, v30, v98, 1
	v_add_lshl_u32 v113, v34, v99, 1
	v_add_lshl_u32 v115, v18, v101, 1
	v_add_u32_e32 v55, 0, v104
	v_add_u32_e32 v57, 0, v105
	v_add_u32_e32 v59, 0, v106
	v_add_u32_e32 v61, 0, v107
	v_add_u32_e32 v62, 0, v109
	v_add_u32_e32 v63, 0, v111
	v_add_u32_e32 v70, 0, v113
	v_add_u32_e32 v71, 0, v115
	ds_read_b128 v[4:7], v55 offset:34816
	ds_read_b128 v[8:11], v57 offset:34816
	ds_read_b128 v[12:15], v59 offset:34816
	ds_read_b128 v[22:25], v61 offset:34816
	ds_read_b128 v[26:29], v62 offset:34816
	ds_read_b128 v[30:33], v63 offset:34816
	ds_read_b128 v[34:37], v70 offset:34816
	ds_read_b128 v[38:41], v71 offset:34816
	v_bitop3_b32 v42, v16, v19, 32 bitop3:0x36
	v_add_lshl_u32 v116, v42, v17, 1
	v_or_b32_e32 v18, 32, v16
	v_add_u32_e32 v73, 0, v116
	s_waitcnt lgkmcnt(7)
	v_mfma_f32_16x16x32_bf16 v[4:7], v[0:3], v[4:7], 0
	ds_read_b128 v[42:45], v73 offset:34816
	v_or_b32_e32 v102, 0x60, v16
	v_mul_lo_u32 v58, v58, s1
	s_waitcnt lgkmcnt(7)
	v_mfma_f32_16x16x32_bf16 v[8:11], v[0:3], v[8:11], 0
	v_add_lshl_u32 v58, v134, v58, 1
	s_waitcnt lgkmcnt(6)
	v_mfma_f32_16x16x32_bf16 v[12:15], v[0:3], v[12:15], 0
	s_waitcnt lgkmcnt(5)
	v_mfma_f32_16x16x32_bf16 v[22:25], v[0:3], v[22:25], 0
	s_waitcnt lgkmcnt(4)
	v_mfma_f32_16x16x32_bf16 v[26:29], v[0:3], v[26:29], 0
	s_waitcnt lgkmcnt(3)
	v_mfma_f32_16x16x32_bf16 v[30:33], v[0:3], v[30:33], 0
	s_waitcnt lgkmcnt(2)
	v_mfma_f32_16x16x32_bf16 v[34:37], v[0:3], v[34:37], 0
	s_waitcnt lgkmcnt(1)
	v_mfma_f32_16x16x32_bf16 v[0:3], v[0:3], v[38:41], 0
	v_xad_u32 v38, v51, v18, v50
	v_lshl_add_u32 v72, v38, 1, 0
	ds_read_b128 v[38:41], v72
	s_waitcnt lgkmcnt(0)
	v_mfma_f32_16x16x32_bf16 v[4:7], v[38:41], v[42:45], v[4:7]
	v_bitop3_b32 v42, v141, v18, 24 bitop3:0x6c
	v_add_lshl_u32 v117, v42, v20, 1
	v_add_u32_e32 v74, 0, v117
	ds_read_b128 v[42:45], v74 offset:34816
	s_waitcnt lgkmcnt(0)
	v_mfma_f32_16x16x32_bf16 v[8:11], v[38:41], v[42:45], v[8:11]
	v_bitop3_b32 v42, v114, v18, 40 bitop3:0x6c
	v_add_lshl_u32 v118, v42, v21, 1
	v_add_u32_e32 v75, 0, v118
	ds_read_b128 v[42:45], v75 offset:34816
	s_waitcnt lgkmcnt(0)
	v_mfma_f32_16x16x32_bf16 v[12:15], v[38:41], v[42:45], v[12:15]
	v_bitop3_b32 v42, v95, v18, 56 bitop3:0x6c
	v_add_lshl_u32 v119, v42, v96, 1
	v_add_u32_e32 v76, 0, v119
	ds_read_b128 v[42:45], v76 offset:34816
	s_waitcnt lgkmcnt(0)
	v_mfma_f32_16x16x32_bf16 v[22:25], v[38:41], v[42:45], v[22:25]
	v_bitop3_b32 v42, v112, v18, s39 bitop3:0x6c
	v_add_lshl_u32 v120, v42, v97, 1
	v_add_u32_e32 v77, 0, v120
	ds_read_b128 v[42:45], v77 offset:34816
	s_waitcnt lgkmcnt(0)
	v_mfma_f32_16x16x32_bf16 v[26:29], v[38:41], v[42:45], v[26:29]
	v_bitop3_b32 v42, v110, v18, s40 bitop3:0x6c
	v_add_lshl_u32 v121, v42, v98, 1
	v_add_u32_e32 v78, 0, v121
	ds_read_b128 v[42:45], v78 offset:34816
	s_waitcnt lgkmcnt(0)
	v_mfma_f32_16x16x32_bf16 v[42:45], v[38:41], v[42:45], v[30:33]
	s_nop 2
	v_bitop3_b32 v30, v108, v18, s41 bitop3:0x6c
	v_add_lshl_u32 v122, v30, v99, 1
	v_add_u32_e32 v79, 0, v122
	ds_read_b128 v[30:33], v79 offset:34816
	v_bitop3_b32 v18, v100, v18, s0 bitop3:0x6c
	v_add_lshl_u32 v123, v18, v101, 1
	v_add_u32_e32 v80, 0, v123
	s_waitcnt lgkmcnt(0)
	v_mfma_f32_16x16x32_bf16 v[46:49], v[38:41], v[30:33], v[34:37]
	ds_read_b128 v[30:33], v80 offset:34816
	v_or_b32_e32 v18, 64, v16
	s_waitcnt lgkmcnt(0)
	v_mfma_f32_16x16x32_bf16 v[142:145], v[38:41], v[30:33], v[0:3]
	s_nop 2
	v_xad_u32 v0, v51, v18, v50
	v_lshl_add_u32 v81, v0, 1, 0
	ds_read_b128 v[146:149], v81
	v_bitop3_b32 v0, v16, v19, 64 bitop3:0x36
	v_add_lshl_u32 v124, v0, v17, 1
	v_add_u32_e32 v82, 0, v124
	ds_read_b128 v[0:3], v82 offset:34816
	s_waitcnt lgkmcnt(0)
	v_mfma_f32_16x16x32_bf16 v[0:3], v[146:149], v[0:3], v[4:7]
	s_nop 2
	v_bitop3_b32 v4, v141, v18, 24 bitop3:0x6c
	v_add_lshl_u32 v125, v4, v20, 1
	v_add_u32_e32 v83, 0, v125
	ds_read_b128 v[4:7], v83 offset:34816
	s_waitcnt lgkmcnt(0)
	v_mfma_f32_16x16x32_bf16 v[4:7], v[146:149], v[4:7], v[8:11]
	s_nop 2
	v_bitop3_b32 v8, v114, v18, 40 bitop3:0x6c
	v_add_lshl_u32 v126, v8, v21, 1
	v_add_u32_e32 v84, 0, v126
	ds_read_b128 v[8:11], v84 offset:34816
	s_waitcnt lgkmcnt(0)
	v_mfma_f32_16x16x32_bf16 v[8:11], v[146:149], v[8:11], v[12:15]
	s_nop 2
	v_bitop3_b32 v12, v95, v18, 56 bitop3:0x6c
	v_add_lshl_u32 v127, v12, v96, 1
	v_add_u32_e32 v85, 0, v127
	ds_read_b128 v[12:15], v85 offset:34816
	s_waitcnt lgkmcnt(0)
	v_mfma_f32_16x16x32_bf16 v[12:15], v[146:149], v[12:15], v[22:25]
	s_nop 2
	v_bitop3_b32 v22, v112, v18, s39 bitop3:0x6c
	v_add_lshl_u32 v128, v22, v97, 1
	v_add_u32_e32 v86, 0, v128
	ds_read_b128 v[22:25], v86 offset:34816
	s_waitcnt lgkmcnt(0)
	v_mfma_f32_16x16x32_bf16 v[32:35], v[146:149], v[22:25], v[26:29]
	v_bitop3_b32 v22, v110, v18, s40 bitop3:0x6c
	v_add_lshl_u32 v129, v22, v98, 1
	v_add_u32_e32 v87, 0, v129
	ds_read_b128 v[22:25], v87 offset:34816
	s_waitcnt lgkmcnt(0)
; #define LAS __attribute__((address_space(3)))
; DI void out_unit(const Inputs& in, int l, unsigned char* ws, int half, int u, LAS unsigned char* lds, int tid) {
;     ...
;     zero8(F); mma16(F, Qt, 16 * wave, Kt, lane);
; #pragma unroll
;     for (int cg = 0; cg < 8; ++cg)
; #pragma unroll
;         for (int r = 0; r < 4; ++r) { const int i = 16 * wave + 4 * quad + r, j = 16 * cg + l15, df = i - j;
;             const float fac = df >= 0 ? __expf((float)df * lgf) : __expf((float)(-df) * lgb);
;             ((LAS bf16_t*)Ps)[sw(4 * quad + r, j)] = f2bf(F[cg][r] * fac); }
	v_mfma_f32_16x16x32_bf16 v[36:39], v[146:149], v[22:25], v[42:45]
	v_bitop3_b32 v22, v108, v18, s41 bitop3:0x6c
	v_add_lshl_u32 v130, v22, v99, 1
	v_add_u32_e32 v88, 0, v130
	ds_read_b128 v[22:25], v88 offset:34816
	v_bitop3_b32 v18, v100, v18, s0 bitop3:0x6c
	v_bitop3_b32 v16, v16, v19, s13 bitop3:0x36
	v_add_lshl_u32 v131, v18, v101, 1
	v_xad_u32 v18, v51, v102, v50
	v_add_lshl_u32 v132, v16, v17, 1
	v_add_u32_e32 v89, 0, v131
	v_lshl_add_u32 v90, v18, 1, 0
	v_add_u32_e32 v92, 0, v132
	ds_read_b128 v[16:19], v92 offset:34816
	s_waitcnt lgkmcnt(1)
	v_mfma_f32_16x16x32_bf16 v[40:43], v[146:149], v[22:25], v[46:49]
	ds_read_b128 v[22:25], v89 offset:34816
	s_ashr_i32 s13, s12, 31
	s_lshl_b64 s[16:17], s[12:13], 15
	ds_read_b128 v[48:51], v90
	s_waitcnt lgkmcnt(0)
	v_mfma_f32_16x16x32_bf16 v[28:31], v[48:51], v[16:19], v[0:3]
	s_nop 2
	v_bitop3_b32 v0, v141, v102, 24 bitop3:0x6c
	v_add_lshl_u32 v137, v0, v20, 1
	v_add_u32_e32 v93, 0, v137
	ds_read_b128 v[0:3], v93 offset:34816
	v_mfma_f32_16x16x32_bf16 v[44:47], v[146:149], v[22:25], v[142:145]
	s_add_u32 s16, s22, s16
	s_addc_u32 s17, s23, s17
	s_waitcnt lgkmcnt(0)
	v_mfma_f32_16x16x32_bf16 v[24:27], v[48:51], v[0:3], v[4:7]
	v_bitop3_b32 v0, v114, v102, 40 bitop3:0x6c
	v_add_lshl_u32 v138, v0, v21, 1
	v_add_u32_e32 v94, 0, v138
	ds_read_b128 v[0:3], v94 offset:34816
	s_waitcnt lgkmcnt(0)
	v_mfma_f32_16x16x32_bf16 v[20:23], v[48:51], v[0:3], v[8:11]
	v_bitop3_b32 v0, v95, v102, 56 bitop3:0x6c
	v_add_lshl_u32 v139, v0, v96, 1
	v_add_u32_e32 v95, 0, v139
	ds_read_b128 v[0:3], v95 offset:34816
	s_waitcnt lgkmcnt(0)
	v_mfma_f32_16x16x32_bf16 v[16:19], v[48:51], v[0:3], v[12:15]
	v_bitop3_b32 v0, v112, v102, s39 bitop3:0x6c
	v_add_lshl_u32 v140, v0, v97, 1
	v_add_u32_e32 v96, 0, v140
	ds_read_b128 v[0:3], v96 offset:34816
	s_waitcnt lgkmcnt(0)
	v_mfma_f32_16x16x32_bf16 v[12:15], v[48:51], v[0:3], v[32:35]
	v_bitop3_b32 v0, v110, v102, s40 bitop3:0x6c
	s_nop 1
	v_add_lshl_u32 v32, v0, v98, 1
	v_add_u32_e32 v97, 0, v32
	ds_read_b128 v[0:3], v97 offset:34816
	s_waitcnt lgkmcnt(0)
	v_mfma_f32_16x16x32_bf16 v[8:11], v[48:51], v[0:3], v[36:39]
	v_bitop3_b32 v0, v108, v102, s41 bitop3:0x6c
	v_add_lshl_u32 v33, v0, v99, 1
	v_add_u32_e32 v98, 0, v33
	ds_read_b128 v[0:3], v98 offset:34816
	v_lshrrev_b32_e32 v37, 2, v66
	s_waitcnt lgkmcnt(0)
	v_mfma_f32_16x16x32_bf16 v[4:7], v[48:51], v[0:3], v[40:43]
	v_bitop3_b32 v0, v100, v102, s0 bitop3:0x6c
	v_and_b32_e32 v36, 12, v37
	v_add_lshl_u32 v34, v0, v101, 1
	v_or_b32_e32 v101, v36, v69
	v_sub_u32_e32 v38, v101, v68
	v_sub_u32_e32 v39, 0, v38
	v_max_i32_e32 v39, v38, v39
	v_cvt_f32_u32_e32 v39, v39
	v_cmp_gt_i32_e32 vcc, 0, v38
	v_add_u32_e32 v99, 0, v34
	ds_read_b128 v[0:3], v99 offset:34816
	v_cndmask_b32_e32 v38, v60, v67, vcc
	v_mul_f32_e32 v38, v38, v39
	v_mul_f32_e32 v38, 0xbfb8aa3b, v38
	v_exp_f32_e32 v38, v38
	v_and_b32_e32 v35, 7, v66
	v_bitop3_b32 v37, v37, 8, v66 bitop3:0x48
	v_lshl_add_u32 v35, v35, 1, v65
	v_lshlrev_b32_e32 v37, 1, v37
	v_mul_f32_e32 v28, v38, v28
	v_mul_u32_u24_e32 v103, 0x110, v36
	s_waitcnt lgkmcnt(0)
	v_mfma_f32_16x16x32_bf16 v[0:3], v[48:51], v[0:3], v[44:47]
	v_cvt_pk_bf16_f32 v28, v28, s0
	v_add3_u32 v37, v35, v37, v103
	v_or_b32_e32 v48, 1, v101
	ds_write_b16 v37, v28
	v_sub_u32_e32 v28, v48, v68
	v_sub_u32_e32 v38, 0, v28
	v_max_i32_e32 v38, v28, v38
	v_cvt_f32_u32_e32 v38, v38
	v_cmp_gt_i32_e32 vcc, 0, v28
	v_or_b32_e32 v102, 2, v101
	v_or_b32_e32 v100, 3, v101
	v_cndmask_b32_e32 v28, v60, v67, vcc
	v_mul_f32_e32 v28, v28, v38
	v_mul_f32_e32 v28, 0xbfb8aa3b, v28
	v_exp_f32_e32 v28, v28
	v_add_u32_e32 v50, s82, v113
	v_add_u32_e32 v49, s82, v115
	v_add_u32_e32 v51, s82, v116
	v_mul_f32_e32 v28, v28, v29
	v_cvt_pk_bf16_f32 v28, v28, s0
	ds_write_b16 v37, v28 offset:272
	v_sub_u32_e32 v28, v102, v68
	v_sub_u32_e32 v29, 0, v28
	v_max_i32_e32 v29, v28, v29
	v_cvt_f32_u32_e32 v29, v29
	v_cmp_gt_i32_e32 vcc, 0, v28
	v_add_u32_e32 v113, s82, v121
	v_add_u32_e32 v115, s82, v122
	v_cndmask_b32_e32 v28, v60, v67, vcc
	v_mul_f32_e32 v28, v28, v29
	v_mul_f32_e32 v28, 0xbfb8aa3b, v28
	v_exp_f32_e32 v28, v28
	v_add_u32_e32 v121, s82, v128
	v_add_u32_e32 v122, s82, v129
	v_add_u32_e32 v128, s82, v139
	v_mul_f32_e32 v28, v28, v30
	v_cvt_pk_bf16_f32 v28, v28, s0
	ds_write_b16 v37, v28 offset:544
	v_sub_u32_e32 v28, v100, v68
	v_sub_u32_e32 v29, 0, v28
	v_max_i32_e32 v29, v28, v29
	v_cvt_f32_u32_e32 v29, v29
	v_cmp_gt_i32_e32 vcc, 0, v28
	v_add_u32_e32 v129, s82, v140
	s_nop 0
	v_cndmask_b32_e32 v28, v60, v67, vcc
	v_mul_f32_e32 v28, v28, v29
	v_sub_u32_e32 v29, v101, v141
	v_sub_u32_e32 v30, 0, v29
	v_max_i32_e32 v30, v29, v30
	v_cvt_f32_u32_e32 v30, v30
	v_mul_f32_e32 v28, 0xbfb8aa3b, v28
	v_cmp_gt_i32_e32 vcc, 0, v29
	v_exp_f32_e32 v28, v28
	s_nop 0
	v_cndmask_b32_e32 v29, v60, v67, vcc
	v_mul_f32_e32 v29, v29, v30
	v_mul_f32_e32 v29, 0xbfb8aa3b, v29
	v_exp_f32_e32 v29, v29
	v_mul_f32_e32 v28, v28, v31
	v_cvt_pk_bf16_f32 v28, v28, s0
	ds_write_b16 v37, v28 offset:816
	v_bitop3_b32 v28, v141, 24, v36 bitop3:0x48
	v_lshlrev_b32_e32 v28, 1, v28
	v_mul_f32_e32 v24, v29, v24
	v_cvt_pk_bf16_f32 v24, v24, s0
	v_add3_u32 v28, v35, v28, v103
	ds_write_b16 v28, v24
	v_sub_u32_e32 v24, v48, v141
	v_sub_u32_e32 v29, 0, v24
	v_max_i32_e32 v29, v24, v29
	v_cvt_f32_u32_e32 v29, v29
	v_cmp_gt_i32_e32 vcc, 0, v24
	s_nop 1
	v_cndmask_b32_e32 v24, v60, v67, vcc
	v_mul_f32_e32 v24, v24, v29
	v_mul_f32_e32 v24, 0xbfb8aa3b, v24
	v_exp_f32_e32 v24, v24
	s_nop 0
	v_mul_f32_e32 v24, v24, v25
	v_cvt_pk_bf16_f32 v24, v24, s0
	ds_write_b16 v28, v24 offset:272
	v_sub_u32_e32 v24, v102, v141
	v_sub_u32_e32 v25, 0, v24
	v_max_i32_e32 v25, v24, v25
; #define LAS __attribute__((address_space(3)))
; DI void out_unit(const Inputs& in, int l, unsigned char* ws, int half, int u, LAS unsigned char* lds, int tid) {
;     ...
;     for (int cg = 0; cg < 8; ++cg)
; #pragma unroll
;         for (int r = 0; r < 4; ++r) { const int i = 16 * wave + 4 * quad + r, j = 16 * cg + l15, df = i - j;
;             const float fac = df >= 0 ? __expf((float)df * lgf) : __expf((float)(-df) * lgb);
;             ((LAS bf16_t*)Ps)[sw(4 * quad + r, j)] = f2bf(F[cg][r] * fac); }
	v_cvt_f32_u32_e32 v25, v25
	v_cmp_gt_i32_e32 vcc, 0, v24
	s_nop 1
	v_cndmask_b32_e32 v24, v60, v67, vcc
	v_mul_f32_e32 v24, v24, v25
	v_mul_f32_e32 v24, 0xbfb8aa3b, v24
	v_exp_f32_e32 v24, v24
	s_nop 0
	v_mul_f32_e32 v24, v24, v26
	v_cvt_pk_bf16_f32 v24, v24, s0
	ds_write_b16 v28, v24 offset:544
	v_sub_u32_e32 v24, v100, v141
	v_sub_u32_e32 v25, 0, v24
	v_max_i32_e32 v25, v24, v25
	v_cvt_f32_u32_e32 v25, v25
	v_cmp_gt_i32_e32 vcc, 0, v24
	s_nop 1
	v_cndmask_b32_e32 v24, v60, v67, vcc
	v_mul_f32_e32 v24, v24, v25
	v_sub_u32_e32 v25, v101, v114
	v_sub_u32_e32 v26, 0, v25
	v_max_i32_e32 v26, v25, v26
	v_cvt_f32_u32_e32 v26, v26
	v_mul_f32_e32 v24, 0xbfb8aa3b, v24
	v_cmp_gt_i32_e32 vcc, 0, v25
	v_exp_f32_e32 v24, v24
	s_nop 0
	v_cndmask_b32_e32 v25, v60, v67, vcc
	v_mul_f32_e32 v25, v25, v26
	v_mul_f32_e32 v25, 0xbfb8aa3b, v25
	v_exp_f32_e32 v25, v25
	v_mul_f32_e32 v24, v24, v27
	v_cvt_pk_bf16_f32 v24, v24, s0
	ds_write_b16 v28, v24 offset:816
	v_bitop3_b32 v24, v114, 40, v36 bitop3:0x48
	v_lshlrev_b32_e32 v24, 1, v24
	v_mul_f32_e32 v20, v25, v20
	v_cvt_pk_bf16_f32 v20, v20, s0
	v_add3_u32 v24, v35, v24, v103
	ds_write_b16 v24, v20
	v_sub_u32_e32 v20, v48, v114
	v_sub_u32_e32 v25, 0, v20
	v_max_i32_e32 v25, v20, v25
	v_cvt_f32_u32_e32 v25, v25
	v_cmp_gt_i32_e32 vcc, 0, v20
	s_nop 1
	v_cndmask_b32_e32 v20, v60, v67, vcc
	v_mul_f32_e32 v20, v20, v25
	v_mul_f32_e32 v20, 0xbfb8aa3b, v20
	v_exp_f32_e32 v20, v20
	s_nop 0
	v_mul_f32_e32 v20, v20, v21
	v_cvt_pk_bf16_f32 v20, v20, s0
	ds_write_b16 v24, v20 offset:272
	v_sub_u32_e32 v20, v102, v114
	v_sub_u32_e32 v21, 0, v20
	v_max_i32_e32 v21, v20, v21
	v_cvt_f32_u32_e32 v21, v21
	v_cmp_gt_i32_e32 vcc, 0, v20
	s_nop 1
	v_cndmask_b32_e32 v20, v60, v67, vcc
	v_mul_f32_e32 v20, v20, v21
	v_mul_f32_e32 v20, 0xbfb8aa3b, v20
	v_exp_f32_e32 v20, v20
	s_nop 0
	v_mul_f32_e32 v20, v20, v22
	v_cvt_pk_bf16_f32 v20, v20, s0
	ds_write_b16 v24, v20 offset:544
	v_sub_u32_e32 v20, v100, v114
	v_sub_u32_e32 v21, 0, v20
	v_max_i32_e32 v21, v20, v21
	v_cvt_f32_u32_e32 v21, v21
	v_cmp_gt_i32_e32 vcc, 0, v20
	v_add_u32_e32 v114, s82, v104
	s_nop 0
	v_cndmask_b32_e32 v20, v60, v67, vcc
	v_mul_f32_e32 v20, v20, v21
	v_mul_f32_e32 v20, 0xbfb8aa3b, v20
	v_exp_f32_e32 v20, v20
	s_nop 0
	v_mul_f32_e32 v20, v20, v23
	v_cvt_pk_bf16_f32 v20, v20, s0
	ds_write_b16 v24, v20 offset:816
	v_or_b32_e32 v20, 48, v68
	v_sub_u32_e32 v22, v101, v20
	v_sub_u32_e32 v23, 0, v22
	v_max_i32_e32 v23, v22, v23
	v_cvt_f32_u32_e32 v23, v23
	v_cmp_gt_i32_e32 vcc, 0, v22
	v_bitop3_b32 v21, v20, 56, v36 bitop3:0x48
	v_lshlrev_b32_e32 v21, 1, v21
	v_cndmask_b32_e32 v22, v60, v67, vcc
	v_mul_f32_e32 v22, v22, v23
	v_mul_f32_e32 v22, 0xbfb8aa3b, v22
	v_exp_f32_e32 v22, v22
	v_add3_u32 v21, v35, v21, v103
	v_mul_f32_e32 v16, v22, v16
	v_cvt_pk_bf16_f32 v16, v16, s0
	ds_write_b16 v21, v16
	v_sub_u32_e32 v16, v48, v20
	v_sub_u32_e32 v22, 0, v16
	v_max_i32_e32 v22, v16, v22
	v_cvt_f32_u32_e32 v22, v22
	v_cmp_gt_i32_e32 vcc, 0, v16
	s_nop 1
	v_cndmask_b32_e32 v16, v60, v67, vcc
	v_mul_f32_e32 v16, v16, v22
	v_mul_f32_e32 v16, 0xbfb8aa3b, v16
	v_exp_f32_e32 v16, v16
	s_nop 0
	v_mul_f32_e32 v16, v16, v17
	v_cvt_pk_bf16_f32 v16, v16, s0
	ds_write_b16 v21, v16 offset:272
	v_sub_u32_e32 v16, v102, v20
	v_sub_u32_e32 v17, 0, v16
	v_max_i32_e32 v17, v16, v17
	v_cvt_f32_u32_e32 v17, v17
	v_cmp_gt_i32_e32 vcc, 0, v16
	s_nop 1
	v_cndmask_b32_e32 v16, v60, v67, vcc
	v_mul_f32_e32 v16, v16, v17
	v_mul_f32_e32 v16, 0xbfb8aa3b, v16
	v_exp_f32_e32 v16, v16
	s_nop 0
	v_mul_f32_e32 v16, v16, v18
	v_cvt_pk_bf16_f32 v16, v16, s0
	ds_write_b16 v21, v16 offset:544
	v_sub_u32_e32 v16, v100, v20
	v_sub_u32_e32 v17, 0, v16
	v_max_i32_e32 v17, v16, v17
	v_cvt_f32_u32_e32 v17, v17
	v_cmp_gt_i32_e32 vcc, 0, v16
	s_nop 1
	v_cndmask_b32_e32 v16, v60, v67, vcc
	v_mul_f32_e32 v16, v16, v17
	v_sub_u32_e32 v17, v101, v112
	v_sub_u32_e32 v18, 0, v17
	v_max_i32_e32 v18, v17, v18
	v_cvt_f32_u32_e32 v18, v18
	v_mul_f32_e32 v16, 0xbfb8aa3b, v16
	v_cmp_gt_i32_e32 vcc, 0, v17
	v_exp_f32_e32 v16, v16
	s_nop 0
	v_cndmask_b32_e32 v17, v60, v67, vcc
	v_mul_f32_e32 v17, v17, v18
	v_mul_f32_e32 v17, 0xbfb8aa3b, v17
	v_exp_f32_e32 v17, v17
	v_mul_f32_e32 v16, v16, v19
	v_cvt_pk_bf16_f32 v16, v16, s0
	ds_write_b16 v21, v16 offset:816
	v_bitop3_b32 v16, v112, s39, v36 bitop3:0x48
	v_lshlrev_b32_e32 v16, 1, v16
	v_mul_f32_e32 v12, v17, v12
	v_cvt_pk_bf16_f32 v12, v12, s0
	v_add3_u32 v16, v35, v16, v103
	ds_write_b16 v16, v12
	v_sub_u32_e32 v12, v48, v112
	v_sub_u32_e32 v17, 0, v12
	v_max_i32_e32 v17, v12, v17
	v_cvt_f32_u32_e32 v17, v17
	v_cmp_gt_i32_e32 vcc, 0, v12
	s_nop 1
	v_cndmask_b32_e32 v12, v60, v67, vcc
	v_mul_f32_e32 v12, v12, v17
	v_mul_f32_e32 v12, 0xbfb8aa3b, v12
	v_exp_f32_e32 v12, v12
	s_nop 0
	v_mul_f32_e32 v12, v12, v13
	v_cvt_pk_bf16_f32 v12, v12, s0
	ds_write_b16 v16, v12 offset:272
	v_sub_u32_e32 v12, v102, v112
	v_sub_u32_e32 v13, 0, v12
	v_max_i32_e32 v13, v12, v13
	v_cvt_f32_u32_e32 v13, v13
	v_cmp_gt_i32_e32 vcc, 0, v12
	s_nop 1
	v_cndmask_b32_e32 v12, v60, v67, vcc
	v_mul_f32_e32 v12, v12, v13
	v_mul_f32_e32 v12, 0xbfb8aa3b, v12
	v_exp_f32_e32 v12, v12
	s_nop 0
	v_mul_f32_e32 v12, v12, v14
	v_cvt_pk_bf16_f32 v12, v12, s0
	ds_write_b16 v16, v12 offset:544
	v_sub_u32_e32 v12, v100, v112
	v_sub_u32_e32 v13, 0, v12
	v_max_i32_e32 v13, v12, v13
	v_cvt_f32_u32_e32 v13, v13
	v_cmp_gt_i32_e32 vcc, 0, v12
	v_add_u32_e32 v112, s82, v105
	v_add_u32_e32 v105, s82, v117
	v_cndmask_b32_e32 v12, v60, v67, vcc
	v_mul_f32_e32 v12, v12, v13
	v_sub_u32_e32 v13, v101, v110
	v_sub_u32_e32 v14, 0, v13
	v_max_i32_e32 v14, v13, v14
	v_cvt_f32_u32_e32 v14, v14
	v_mul_f32_e32 v12, 0xbfb8aa3b, v12
; #define LAS __attribute__((address_space(3)))
; #define LDS_WAIT() asm volatile("s_waitcnt lgkmcnt(0)" ::: "memory")
; DI void out_unit(const Inputs& in, int l, unsigned char* ws, int half, int u, LAS unsigned char* lds, int tid) {
;     ...
;         for (int r = 0; r < 4; ++r) { const int i = 16 * wave + 4 * quad + r, j = 16 * cg + l15, df = i - j;
;             const float fac = df >= 0 ? __expf((float)df * lgf) : __expf((float)(-df) * lgb);
;             ((LAS bf16_t*)Ps)[sw(4 * quad + r, j)] = f2bf(F[cg][r] * fac); }
;     LDS_WAIT();
;     zero8(O); mma16(O, Ps, 0, VTt, lane);
	v_cmp_gt_i32_e32 vcc, 0, v13
	v_exp_f32_e32 v12, v12
	v_add_u32_e32 v117, s82, v124
	v_cndmask_b32_e32 v13, v60, v67, vcc
	v_mul_f32_e32 v13, v13, v14
	v_mul_f32_e32 v13, 0xbfb8aa3b, v13
	v_exp_f32_e32 v13, v13
	v_mul_f32_e32 v12, v12, v15
	v_cvt_pk_bf16_f32 v12, v12, s0
	ds_write_b16 v16, v12 offset:816
	v_bitop3_b32 v12, v110, s40, v36 bitop3:0x48
	v_lshlrev_b32_e32 v12, 1, v12
	v_mul_f32_e32 v8, v13, v8
	v_cvt_pk_bf16_f32 v8, v8, s0
	v_add3_u32 v12, v35, v12, v103
	ds_write_b16 v12, v8
	v_sub_u32_e32 v8, v48, v110
	v_sub_u32_e32 v13, 0, v8
	v_max_i32_e32 v13, v8, v13
	v_cvt_f32_u32_e32 v13, v13
	v_cmp_gt_i32_e32 vcc, 0, v8
	s_nop 1
	v_cndmask_b32_e32 v8, v60, v67, vcc
	v_mul_f32_e32 v8, v8, v13
	v_mul_f32_e32 v8, 0xbfb8aa3b, v8
	v_exp_f32_e32 v8, v8
	s_nop 0
	v_mul_f32_e32 v8, v8, v9
	v_cvt_pk_bf16_f32 v8, v8, s0
	ds_write_b16 v12, v8 offset:272
	v_sub_u32_e32 v8, v102, v110
	v_sub_u32_e32 v9, 0, v8
	v_max_i32_e32 v9, v8, v9
	v_cvt_f32_u32_e32 v9, v9
	v_cmp_gt_i32_e32 vcc, 0, v8
	s_nop 1
	v_cndmask_b32_e32 v8, v60, v67, vcc
	v_mul_f32_e32 v8, v8, v9
	v_mul_f32_e32 v8, 0xbfb8aa3b, v8
	v_exp_f32_e32 v8, v8
	s_nop 0
	v_mul_f32_e32 v8, v8, v10
	v_cvt_pk_bf16_f32 v8, v8, s0
	ds_write_b16 v12, v8 offset:544
	v_sub_u32_e32 v8, v100, v110
	v_sub_u32_e32 v9, 0, v8
	v_max_i32_e32 v9, v8, v9
	v_cvt_f32_u32_e32 v9, v9
	v_cmp_gt_i32_e32 vcc, 0, v8
	v_add_u32_e32 v110, s82, v106
	v_add_u32_e32 v106, s82, v109
	v_cndmask_b32_e32 v8, v60, v67, vcc
	v_mul_f32_e32 v8, v8, v9
	v_sub_u32_e32 v9, v101, v108
	v_sub_u32_e32 v10, 0, v9
	v_max_i32_e32 v10, v9, v10
	v_cvt_f32_u32_e32 v10, v10
	v_mul_f32_e32 v8, 0xbfb8aa3b, v8
	v_cmp_gt_i32_e32 vcc, 0, v9
	v_exp_f32_e32 v8, v8
	v_add_u32_e32 v109, s82, v119
	v_cndmask_b32_e32 v9, v60, v67, vcc
	v_mul_f32_e32 v9, v9, v10
	v_mul_f32_e32 v9, 0xbfb8aa3b, v9
	v_exp_f32_e32 v9, v9
	v_mul_f32_e32 v8, v8, v11
	v_cvt_pk_bf16_f32 v8, v8, s0
	ds_write_b16 v12, v8 offset:816
	v_bitop3_b32 v8, v108, s41, v36 bitop3:0x48
	v_lshlrev_b32_e32 v8, 1, v8
	v_mul_f32_e32 v4, v9, v4
	v_cvt_pk_bf16_f32 v4, v4, s0
	v_add3_u32 v8, v35, v8, v103
	ds_write_b16 v8, v4
	v_sub_u32_e32 v4, v48, v108
	v_sub_u32_e32 v9, 0, v4
	v_max_i32_e32 v9, v4, v9
	v_cvt_f32_u32_e32 v9, v9
	v_cmp_gt_i32_e32 vcc, 0, v4
	v_add_u32_e32 v119, s82, v126
	v_add_u32_e32 v126, s82, v137
	v_cndmask_b32_e32 v4, v60, v67, vcc
	v_mul_f32_e32 v4, v4, v9
	v_mul_f32_e32 v4, 0xbfb8aa3b, v4
	v_exp_f32_e32 v4, v4
	s_nop 0
	v_mul_f32_e32 v4, v4, v5
	v_cvt_pk_bf16_f32 v4, v4, s0
	ds_write_b16 v8, v4 offset:272
	v_sub_u32_e32 v4, v102, v108
	v_sub_u32_e32 v5, 0, v4
	v_max_i32_e32 v5, v4, v5
	v_cvt_f32_u32_e32 v5, v5
	v_cmp_gt_i32_e32 vcc, 0, v4
	s_nop 1
	v_cndmask_b32_e32 v4, v60, v67, vcc
	v_mul_f32_e32 v4, v4, v5
	v_mul_f32_e32 v4, 0xbfb8aa3b, v4
	v_exp_f32_e32 v4, v4
	s_nop 0
	v_mul_f32_e32 v4, v4, v6
	v_cvt_pk_bf16_f32 v4, v4, s0
	ds_write_b16 v8, v4 offset:544
	v_sub_u32_e32 v4, v100, v108
	v_sub_u32_e32 v5, 0, v4
	v_max_i32_e32 v5, v4, v5
	v_cvt_f32_u32_e32 v5, v5
	v_cmp_gt_i32_e32 vcc, 0, v4
	v_add_u32_e32 v108, s82, v107
	v_add_u32_e32 v107, s82, v118
	v_cndmask_b32_e32 v4, v60, v67, vcc
	v_mul_f32_e32 v4, v4, v5
	v_mul_f32_e32 v4, 0xbfb8aa3b, v4
	v_exp_f32_e32 v4, v4
	v_add_u32_e32 v118, s82, v125
	v_add_u32_e32 v125, s82, v132
	v_mul_f32_e32 v4, v4, v7
	v_cvt_pk_bf16_f32 v4, v4, s0
	ds_write_b16 v8, v4 offset:816
	v_or_b32_e32 v4, 0x70, v68
	v_sub_u32_e32 v6, v101, v4
	v_sub_u32_e32 v7, 0, v6
	v_max_i32_e32 v7, v6, v7
	v_cvt_f32_u32_e32 v7, v7
	v_cmp_gt_i32_e32 vcc, 0, v6
	v_bitop3_b32 v5, v4, s0, v36 bitop3:0x48
	v_lshlrev_b32_e32 v5, 1, v5
	v_cndmask_b32_e32 v6, v60, v67, vcc
	v_mul_f32_e32 v6, v6, v7
	v_mul_f32_e32 v6, 0xbfb8aa3b, v6
	v_exp_f32_e32 v6, v6
	v_add3_u32 v5, v35, v5, v103
	v_add_u32_e32 v35, v65, v116
	v_add_u32_e32 v116, s82, v123
	v_mul_f32_e32 v0, v6, v0
	v_cvt_pk_bf16_f32 v0, v0, s0
	ds_write_b16 v5, v0
	v_sub_u32_e32 v0, v48, v4
	v_sub_u32_e32 v6, 0, v0
	v_max_i32_e32 v6, v0, v6
	v_cvt_f32_u32_e32 v6, v6
	v_cmp_gt_i32_e32 vcc, 0, v0
	v_add_u32_e32 v123, s82, v130
	v_add_u32_e32 v130, s82, v32
	v_cndmask_b32_e32 v0, v60, v67, vcc
	v_mul_f32_e32 v0, v0, v6
	v_mul_f32_e32 v0, 0xbfb8aa3b, v0
	v_exp_f32_e32 v0, v0
	v_cvt_f32_i32_e32 v48, v48
	v_mul_f32_e32 v0, v0, v1
	v_cvt_pk_bf16_f32 v0, v0, s0
	ds_write_b16 v5, v0 offset:272
	v_sub_u32_e32 v0, v102, v4
	v_sub_u32_e32 v1, 0, v0
	v_max_i32_e32 v1, v0, v1
	v_cvt_f32_u32_e32 v1, v1
	v_cmp_gt_i32_e32 vcc, 0, v0
	v_mul_f32_e32 v48, v48, v60
	v_mul_f32_e32 v48, 0xbfb8aa3b, v48
	v_cndmask_b32_e32 v0, v60, v67, vcc
	v_mul_f32_e32 v0, v0, v1
	v_mul_f32_e32 v0, 0xbfb8aa3b, v0
	v_exp_f32_e32 v0, v0
	v_exp_f32_e32 v48, v48
	v_mul_f32_e32 v0, v0, v2
	v_cvt_pk_bf16_f32 v0, v0, s0
	ds_write_b16 v5, v0 offset:544
	v_sub_u32_e32 v0, v100, v4
	v_sub_u32_e32 v1, 0, v0
	v_max_i32_e32 v1, v0, v1
	v_cvt_f32_u32_e32 v1, v1
	v_cmp_gt_i32_e32 vcc, 0, v0
	s_nop 1
	v_cndmask_b32_e32 v0, v60, v67, vcc
	v_mul_f32_e32 v0, v0, v1
	v_mul_f32_e32 v0, 0xbfb8aa3b, v0
	v_exp_f32_e32 v0, v0
	s_nop 0
	v_mul_f32_e32 v0, v0, v3
	v_cvt_pk_bf16_f32 v0, v0, s0
	ds_write_b16 v5, v0 offset:816
	s_waitcnt lgkmcnt(0)
	v_add_u32_e32 v0, v65, v104
	ds_read_b128 v[0:3], v0
	ds_read_b128 v[36:39], v49
	v_add_u32_e32 v104, s82, v111
	ds_read_b128 v[4:7], v114
	ds_read_b128 v[8:11], v112
	ds_read_b128 v[12:15], v110
	ds_read_b128 v[16:19], v108
	ds_read_b128 v[20:23], v106
	ds_read_b128 v[24:27], v104
	ds_read_b128 v[28:31], v50
	s_waitcnt lgkmcnt(6)
	v_mfma_f32_16x16x32_bf16 v[4:7], v[0:3], v[4:7], 0
	ds_read_b128 v[40:43], v51
	v_add_u32_e32 v111, s82, v120
	v_add_u32_e32 v120, s82, v127
	s_waitcnt lgkmcnt(6)
; #define LAS __attribute__((address_space(3)))
; DI void stage_state(LAS unsigned char* dst, const bf16_t* src, int tid) {
;     u32x4 wv[4];
; #pragma unroll
;     for (int k = 0; k < 4; ++k) { const int it = tid + 512 * k, e = it >> 4, d0 = (it & 15) * 8; wv[k] = *(const u32x4*)(src + e * 128 + d0); }
; #pragma unroll
;     for (int k = 0; k < 4; ++k) { const int it = tid + 512 * k, e = it >> 4, d0 = (it & 15) * 8; *(LAS u32x4*)(dst + sw(e, d0) * 2) = wv[k]; }
; }
; DI void out_unit(const Inputs& in, int l, unsigned char* ws, int half, int u, LAS unsigned char* lds, int tid) {
;     ...
;     zero8(O); mma16(O, Ps, 0, VTt, lane);
;     __syncthreads();
;     stage_state(Kt, SS + (size_t)(u * 2 + 0) * 16384, tid); stage_state(VTt, SS + (size_t)(u * 2 + 1) * 16384, tid);
;     __syncthreads();
	v_mfma_f32_16x16x32_bf16 v[8:11], v[0:3], v[8:11], 0
	v_add_u32_e32 v127, s82, v138
	s_waitcnt lgkmcnt(5)
	v_mfma_f32_16x16x32_bf16 v[12:15], v[0:3], v[12:15], 0
	s_waitcnt lgkmcnt(4)
	v_mfma_f32_16x16x32_bf16 v[16:19], v[0:3], v[16:19], 0
	s_waitcnt lgkmcnt(3)
	v_mfma_f32_16x16x32_bf16 v[20:23], v[0:3], v[20:23], 0
	s_waitcnt lgkmcnt(2)
	v_mfma_f32_16x16x32_bf16 v[24:27], v[0:3], v[24:27], 0
	s_waitcnt lgkmcnt(1)
	v_mfma_f32_16x16x32_bf16 v[28:31], v[0:3], v[28:31], 0
	v_mfma_f32_16x16x32_bf16 v[0:3], v[0:3], v[36:39], 0
	ds_read_b128 v[36:39], v35
	v_add_u32_e32 v35, v65, v124
	v_add_u32_e32 v124, s82, v131
	s_waitcnt lgkmcnt(0)
	v_mfma_f32_16x16x32_bf16 v[4:7], v[36:39], v[40:43], v[4:7]
	ds_read_b128 v[40:43], v105
	v_add_u32_e32 v131, s82, v33
	v_lshl_add_u64 v[32:33], s[16:17], 0, v[176:177]
	s_waitcnt lgkmcnt(0)
	v_mfma_f32_16x16x32_bf16 v[8:11], v[36:39], v[40:43], v[8:11]
	ds_read_b128 v[40:43], v107
	s_add_i32 s16, s12, 1
	s_ashr_i32 s17, s16, 31
	s_waitcnt lgkmcnt(0)
	v_mfma_f32_16x16x32_bf16 v[12:15], v[36:39], v[40:43], v[12:15]
	ds_read_b128 v[40:43], v109
	s_lshl_b64 s[16:17], s[16:17], 15
	s_add_u32 s16, s22, s16
	s_waitcnt lgkmcnt(0)
	v_mfma_f32_16x16x32_bf16 v[16:19], v[36:39], v[40:43], v[16:19]
	ds_read_b128 v[40:43], v111
	s_addc_u32 s17, s23, s17
	s_add_i32 s26, s26, s18
	s_waitcnt lgkmcnt(0)
	v_mfma_f32_16x16x32_bf16 v[20:23], v[36:39], v[40:43], v[20:23]
	ds_read_b128 v[40:43], v113
	s_add_i32 s12, s12, s25
	s_cmpk_gt_i32 s26, 0x1ff
	s_waitcnt lgkmcnt(0)
	v_mfma_f32_16x16x32_bf16 v[24:27], v[36:39], v[40:43], v[24:27]
	ds_read_b128 v[40:43], v115
	s_waitcnt lgkmcnt(0)
	v_mfma_f32_16x16x32_bf16 v[28:31], v[36:39], v[40:43], v[28:31]
	ds_read_b128 v[40:43], v116
	s_waitcnt lgkmcnt(0)
	v_mfma_f32_16x16x32_bf16 v[0:3], v[36:39], v[40:43], v[0:3]
	ds_read_b128 v[36:39], v35
	ds_read_b128 v[40:43], v117
	s_waitcnt lgkmcnt(0)
	v_mfma_f32_16x16x32_bf16 v[4:7], v[36:39], v[40:43], v[4:7]
	ds_read_b128 v[40:43], v118
	s_waitcnt lgkmcnt(0)
	v_mfma_f32_16x16x32_bf16 v[8:11], v[36:39], v[40:43], v[8:11]
	ds_read_b128 v[40:43], v119
	s_waitcnt lgkmcnt(0)
	v_mfma_f32_16x16x32_bf16 v[12:15], v[36:39], v[40:43], v[12:15]
	ds_read_b128 v[40:43], v120
	s_waitcnt lgkmcnt(0)
	v_mfma_f32_16x16x32_bf16 v[16:19], v[36:39], v[40:43], v[16:19]
	ds_read_b128 v[40:43], v121
	s_waitcnt lgkmcnt(0)
	v_mfma_f32_16x16x32_bf16 v[20:23], v[36:39], v[40:43], v[20:23]
	ds_read_b128 v[40:43], v122
	s_waitcnt lgkmcnt(0)
	v_mfma_f32_16x16x32_bf16 v[24:27], v[36:39], v[40:43], v[24:27]
	ds_read_b128 v[40:43], v123
	s_waitcnt lgkmcnt(0)
	v_mfma_f32_16x16x32_bf16 v[28:31], v[36:39], v[40:43], v[28:31]
	ds_read_b128 v[40:43], v124
	s_waitcnt lgkmcnt(0)
	v_mfma_f32_16x16x32_bf16 v[36:39], v[36:39], v[40:43], v[0:3]
	s_nop 2
	v_add_u32_e32 v0, v65, v132
	ds_read_b128 v[40:43], v0
	ds_read_b128 v[0:3], v125
	s_waitcnt lgkmcnt(0)
	v_mfma_f32_16x16x32_bf16 v[0:3], v[40:43], v[0:3], v[4:7]
	s_nop 2
	ds_read_b128 v[4:7], v126
	v_add_u32_e32 v132, s82, v34
	v_and_b32_e32 v34, 0xffffff80, v91
	s_waitcnt lgkmcnt(0)
	v_mfma_f32_16x16x32_bf16 v[4:7], v[40:43], v[4:7], v[8:11]
	v_ashrrev_i32_e32 v35, 31, v34
	s_nop 1
	ds_read_b128 v[8:11], v127
	v_add_u32_e32 v91, 0, v58
	s_waitcnt lgkmcnt(0)
	v_mfma_f32_16x16x32_bf16 v[8:11], v[40:43], v[8:11], v[12:15]
	s_nop 2
	ds_read_b128 v[12:15], v128
	s_waitcnt lgkmcnt(0)
	v_mfma_f32_16x16x32_bf16 v[12:15], v[40:43], v[12:15], v[16:19]
	s_nop 2
	ds_read_b128 v[16:19], v129
	s_waitcnt lgkmcnt(0)
	v_mfma_f32_16x16x32_bf16 v[16:19], v[40:43], v[16:19], v[20:23]
	s_nop 2
	ds_read_b128 v[20:23], v130
	s_waitcnt lgkmcnt(0)
	v_mfma_f32_16x16x32_bf16 v[20:23], v[40:43], v[20:23], v[24:27]
	s_nop 2
	ds_read_b128 v[24:27], v131
	s_waitcnt lgkmcnt(0)
	v_mfma_f32_16x16x32_bf16 v[24:27], v[40:43], v[24:27], v[28:31]
	s_nop 2
	ds_read_b128 v[28:31], v132
	s_waitcnt lgkmcnt(0)
	s_barrier
	v_mfma_f32_16x16x32_bf16 v[28:31], v[40:43], v[28:31], v[36:39]
	s_nop 2
	v_lshlrev_b64 v[36:37], 1, v[34:35]
	v_lshl_add_u64 v[38:39], v[32:33], 0, v[36:37]
	global_load_dwordx4 v[44:47], v[38:39], off
	v_add_u32_e32 v38, 0x1000, v34
	v_ashrrev_i32_e32 v39, 31, v38
	v_lshlrev_b64 v[38:39], 1, v[38:39]
	v_lshl_add_u64 v[40:41], v[32:33], 0, v[38:39]
	global_load_dwordx4 v[138:141], v[40:41], off
	v_add_u32_e32 v40, 0x2000, v34
	v_ashrrev_i32_e32 v41, 31, v40
	v_lshlrev_b64 v[40:41], 1, v[40:41]
	v_lshl_add_u64 v[42:43], v[32:33], 0, v[40:41]
	v_add_u32_e32 v34, 0x3000, v34
	global_load_dwordx4 v[142:145], v[42:43], off
	v_ashrrev_i32_e32 v35, 31, v34
	v_lshlrev_b64 v[42:43], 1, v[34:35]
	v_lshl_add_u64 v[32:33], v[32:33], 0, v[42:43]
	global_load_dwordx4 v[32:35], v[32:33], off
	s_waitcnt vmcnt(3)
	ds_write_b128 v91, v[44:47] offset:34816
	v_mul_lo_u32 v44, v56, s1
	v_add_lshl_u32 v56, v135, v44, 1
	v_add_u32_e32 v44, 0, v56
	s_waitcnt vmcnt(2)
	ds_write_b128 v44, v[138:141] offset:34816
	v_mul_lo_u32 v44, v54, s1
	v_add_lshl_u32 v54, v136, v44, 1
	v_add_u32_e32 v44, 0, v54
	s_waitcnt vmcnt(1)
	ds_write_b128 v44, v[142:145] offset:34816
	v_mul_lo_u32 v44, v52, s1
	v_add_lshl_u32 v52, v133, v44, 1
	v_add_u32_e32 v44, 0, v52
	s_waitcnt vmcnt(0)
	ds_write_b128 v44, v[32:35] offset:34816
	v_lshl_add_u64 v[32:33], s[16:17], 0, v[176:177]
	v_lshl_add_u64 v[34:35], v[32:33], 0, v[36:37]
	global_load_dwordx4 v[44:47], v[34:35], off
	v_lshl_add_u64 v[34:35], v[32:33], 0, v[38:39]
	global_load_dwordx4 v[36:39], v[34:35], off
	v_lshl_add_u64 v[34:35], v[32:33], 0, v[40:41]
	global_load_dwordx4 v[134:137], v[34:35], off
	v_lshl_add_u64 v[32:33], v[32:33], 0, v[42:43]
	global_load_dwordx4 v[32:35], v[32:33], off
	v_add_u32_e32 v40, s82, v58
	s_waitcnt vmcnt(3)
	ds_write_b128 v40, v[44:47]
	v_add_u32_e32 v40, s82, v56
	s_waitcnt vmcnt(2)
	ds_write_b128 v40, v[36:39]
	v_add_u32_e32 v36, s82, v54
	s_waitcnt vmcnt(1)
	ds_write_b128 v36, v[134:137]
	v_add_u32_e32 v36, s82, v52
	s_waitcnt vmcnt(0)
	ds_write_b128 v36, v[32:35]
	s_waitcnt lgkmcnt(0)
	s_barrier
; DI void out_unit(const Inputs& in, int l, unsigned char* ws, int half, int u, LAS unsigned char* lds, int tid) {
;     ...
;     zero8(F); mma16(F, Qt, 16 * wave, Kt, lane);
; #pragma unroll
;     for (int r = 0; r < 4; ++r) { const int i = 16 * wave + 4 * quad + r; const float qwf = __expf((float)(i + 1) * lgf);
; #pragma unroll
;         for (int cg = 0; cg < 8; ++cg) O[cg][r] += qwf * F[cg][r]; }
;     zero8(F); mma16(F, Qt, 16 * wave, VTt, lane);
	ds_read_b128 v[32:35], v53
	ds_read_b128 v[36:39], v55 offset:34816
	s_waitcnt lgkmcnt(0)
	v_mfma_f32_16x16x32_bf16 v[40:43], v[32:35], v[36:39], 0
	ds_read_b128 v[36:39], v57 offset:34816
	s_waitcnt lgkmcnt(0)
	v_mfma_f32_16x16x32_bf16 v[44:47], v[32:35], v[36:39], 0
	ds_read_b128 v[36:39], v59 offset:34816
	s_waitcnt lgkmcnt(0)
	v_mfma_f32_16x16x32_bf16 v[52:55], v[32:35], v[36:39], 0
	ds_read_b128 v[36:39], v61 offset:34816
	s_waitcnt lgkmcnt(0)
	v_mfma_f32_16x16x32_bf16 v[56:59], v[32:35], v[36:39], 0
	ds_read_b128 v[36:39], v62 offset:34816
	s_waitcnt lgkmcnt(0)
	v_mfma_f32_16x16x32_bf16 v[134:137], v[32:35], v[36:39], 0
	ds_read_b128 v[36:39], v63 offset:34816
	s_waitcnt lgkmcnt(0)
	v_mfma_f32_16x16x32_bf16 v[138:141], v[32:35], v[36:39], 0
	ds_read_b128 v[36:39], v70 offset:34816
	s_waitcnt lgkmcnt(0)
	v_mfma_f32_16x16x32_bf16 v[142:145], v[32:35], v[36:39], 0
	ds_read_b128 v[36:39], v71 offset:34816
	s_waitcnt lgkmcnt(0)
	v_mfma_f32_16x16x32_bf16 v[146:149], v[32:35], v[36:39], 0
	ds_read_b128 v[36:39], v72
	ds_read_b128 v[70:73], v73 offset:34816
	s_waitcnt lgkmcnt(0)
	v_mfma_f32_16x16x32_bf16 v[70:73], v[36:39], v[70:73], v[40:43]
	s_nop 2
	ds_read_b128 v[40:43], v74 offset:34816
	s_waitcnt lgkmcnt(0)
	v_mfma_f32_16x16x32_bf16 v[44:47], v[36:39], v[40:43], v[44:47]
	ds_read_b128 v[40:43], v75 offset:34816
	s_waitcnt lgkmcnt(0)
	v_mfma_f32_16x16x32_bf16 v[52:55], v[36:39], v[40:43], v[52:55]
	ds_read_b128 v[40:43], v76 offset:34816
	s_waitcnt lgkmcnt(0)
	v_mfma_f32_16x16x32_bf16 v[56:59], v[36:39], v[40:43], v[56:59]
	ds_read_b128 v[40:43], v77 offset:34816
	s_waitcnt lgkmcnt(0)
	v_mfma_f32_16x16x32_bf16 v[74:77], v[36:39], v[40:43], v[134:137]
	ds_read_b128 v[40:43], v78 offset:34816
	s_waitcnt lgkmcnt(0)
	v_mfma_f32_16x16x32_bf16 v[134:137], v[36:39], v[40:43], v[138:141]
	ds_read_b128 v[40:43], v79 offset:34816
	s_waitcnt lgkmcnt(0)
	v_mfma_f32_16x16x32_bf16 v[138:141], v[36:39], v[40:43], v[142:145]
	ds_read_b128 v[40:43], v80 offset:34816
	s_waitcnt lgkmcnt(0)
	v_mfma_f32_16x16x32_bf16 v[142:145], v[36:39], v[40:43], v[146:149]
	ds_read_b128 v[40:43], v81
	ds_read_b128 v[78:81], v82 offset:34816
	s_waitcnt lgkmcnt(0)
	v_mfma_f32_16x16x32_bf16 v[70:73], v[40:43], v[78:81], v[70:73]
	ds_read_b128 v[78:81], v83 offset:34816
	s_waitcnt lgkmcnt(0)
	v_mfma_f32_16x16x32_bf16 v[78:81], v[40:43], v[78:81], v[44:47]
	s_nop 2
	ds_read_b128 v[44:47], v84 offset:34816
	s_waitcnt lgkmcnt(0)
	v_mfma_f32_16x16x32_bf16 v[52:55], v[40:43], v[44:47], v[52:55]
	ds_read_b128 v[44:47], v85 offset:34816
	s_waitcnt lgkmcnt(0)
	v_mfma_f32_16x16x32_bf16 v[56:59], v[40:43], v[44:47], v[56:59]
	ds_read_b128 v[44:47], v86 offset:34816
	s_waitcnt lgkmcnt(0)
	v_mfma_f32_16x16x32_bf16 v[74:77], v[40:43], v[44:47], v[74:77]
	ds_read_b128 v[44:47], v87 offset:34816
	s_waitcnt lgkmcnt(0)
	v_mfma_f32_16x16x32_bf16 v[82:85], v[40:43], v[44:47], v[134:137]
	ds_read_b128 v[44:47], v88 offset:34816
	s_waitcnt lgkmcnt(0)
	v_mfma_f32_16x16x32_bf16 v[134:137], v[40:43], v[44:47], v[138:141]
	ds_read_b128 v[44:47], v89 offset:34816
	s_waitcnt lgkmcnt(0)
	v_mfma_f32_16x16x32_bf16 v[86:89], v[40:43], v[44:47], v[142:145]
	ds_read_b128 v[44:47], v90
	ds_read_b128 v[138:141], v92 offset:34816
	ds_read_b128 v[90:93], v93 offset:34816
	s_waitcnt lgkmcnt(0)
	v_mfma_f32_16x16x32_bf16 v[78:81], v[44:47], v[90:93], v[78:81]
	ds_read_b128 v[90:93], v94 offset:34816
	s_waitcnt lgkmcnt(0)
	v_mfma_f32_16x16x32_bf16 v[52:55], v[44:47], v[90:93], v[52:55]
	ds_read_b128 v[90:93], v95 offset:34816
	s_waitcnt lgkmcnt(0)
	v_mfma_f32_16x16x32_bf16 v[56:59], v[44:47], v[90:93], v[56:59]
	ds_read_b128 v[90:93], v96 offset:34816
	s_waitcnt lgkmcnt(0)
	v_mfma_f32_16x16x32_bf16 v[74:77], v[44:47], v[90:93], v[74:77]
	ds_read_b128 v[90:93], v97 offset:34816
	ds_read_b128 v[94:97], v99 offset:34816
	s_nop 2
	v_fma_f32 v12, v48, v56, v12
	s_waitcnt lgkmcnt(1)
	v_mfma_f32_16x16x32_bf16 v[82:85], v[44:47], v[90:93], v[82:85]
	ds_read_b128 v[90:93], v98 offset:34816
	v_fma_f32 v16, v48, v74, v16
	v_mfma_f32_16x16x32_bf16 v[70:73], v[44:47], v[138:141], v[70:73]
	s_nop 4
	v_fma_f32 v20, v48, v82, v20
	s_waitcnt lgkmcnt(1)
	v_mfma_f32_16x16x32_bf16 v[86:89], v[44:47], v[94:97], v[86:89]
	v_fma_f32 v96, v48, v52, v8
	v_fma_f32 v94, v48, v70, v0
	v_cvt_f32_i32_e32 v0, v102
	s_waitcnt lgkmcnt(0)
	v_mfma_f32_16x16x32_bf16 v[90:93], v[44:47], v[90:93], v[134:137]
	v_fma_f32 v95, v48, v78, v4
	s_nop 1
	v_fma_f32 v28, v48, v86, v28
	v_mul_f32_e32 v0, v0, v60
	v_mul_f32_e32 v0, 0xbfb8aa3b, v0
	v_exp_f32_e32 v0, v0
	s_nop 0
	v_fma_f32 v24, v48, v90, v24
	v_fma_f32 v90, v0, v71, v1
	v_fma_f32 v97, v0, v79, v5
	v_fma_f32 v98, v0, v53, v9
	v_fma_f32 v13, v0, v57, v13
	v_fma_f32 v17, v0, v75, v17
	v_fma_f32 v21, v0, v83, v21
	v_fma_f32 v25, v0, v91, v25
	v_fma_f32 v29, v0, v87, v29
	v_cvt_f32_i32_e32 v0, v100
	v_mul_f32_e32 v0, v0, v60
	v_mul_f32_e32 v0, 0xbfb8aa3b, v0
	v_exp_f32_e32 v0, v0
	s_nop 0
	v_fma_f32 v8, v0, v80, v6
	v_fma_f32 v6, v0, v54, v10
	v_add_u32_e32 v10, 4, v101
	v_cvt_f32_i32_e32 v10, v10
	v_fma_f32 v9, v0, v72, v2
	v_fma_f32 v5, v0, v58, v14
	v_fma_f32 v4, v0, v76, v18
	v_mul_f32_e32 v10, v10, v60
	v_mul_f32_e32 v10, 0xbfb8aa3b, v10
	v_exp_f32_e32 v10, v10
	v_fma_f32 v2, v0, v84, v22
	v_fma_f32 v1, v0, v92, v26
	v_fma_f32 v0, v0, v88, v30
	v_fmac_f32_e32 v11, v10, v55
	ds_read_b128 v[52:55], v114
	v_fmac_f32_e32 v7, v10, v81
	v_fmac_f32_e32 v23, v10, v85
	v_fmac_f32_e32 v31, v10, v89
	ds_read_b128 v[78:81], v104
	ds_read_b128 v[82:85], v50
	ds_read_b128 v[86:89], v49
	ds_read_b128 v[48:51], v51
	v_fmac_f32_e32 v15, v10, v59
	s_waitcnt lgkmcnt(4)
; #define LAS __attribute__((address_space(3)))
; DI void out_unit(const Inputs& in, int l, unsigned char* ws, int half, int u, LAS unsigned char* lds, int tid) {
;     ...
;     zero8(F); mma16(F, Qt, 16 * wave, VTt, lane);
;     LAS bf16_t* Pn = (LAS bf16_t*)Ps;
; #pragma unroll
;     for (int r = 0; r < 4; ++r) { const int i = 16 * wave + 4 * quad + r; const float qwb = __expf((float)(128 - i) * lgb);
;         float sm = 0.f;
; #pragma unroll
;         for (int cg = 0; cg < 8; ++cg) { O[cg][r] += qwb * F[cg][r]; sm += O[cg][r]; }
;         sm += __shfl_xor(sm, 1); sm += __shfl_xor(sm, 2); sm += __shfl_xor(sm, 4); sm += __shfl_xor(sm, 8);
;         const float mean = sm * (1.f / 128.f); float vs = 0.f;
; #pragma unroll
;         for (int cg = 0; cg < 8; ++cg) { const float dd = O[cg][r] - mean; vs += dd * dd; }
;         vs += __shfl_xor(vs, 1); vs += __shfl_xor(vs, 2); vs += __shfl_xor(vs, 4); vs += __shfl_xor(vs, 8);
;         const float rinv = __builtin_amdgcn_rsqf(vs * (1.f / 128.f) + EPS);
	v_mfma_f32_16x16x32_bf16 v[52:55], v[32:35], v[52:55], 0
	ds_read_b128 v[56:59], v112
	ds_read_b128 v[60:63], v110
	v_fmac_f32_e32 v19, v10, v77
	ds_read_b128 v[74:77], v106
	s_waitcnt lgkmcnt(3)
	v_mfma_f32_16x16x32_bf16 v[48:51], v[36:39], v[48:51], v[52:55]
	v_fmac_f32_e32 v3, v10, v73
	ds_read_b128 v[70:73], v108
	v_sub_u32_e32 v14, 0x80, v101
	ds_read_b128 v[52:55], v105
	s_waitcnt lgkmcnt(4)
	v_mfma_f32_16x16x32_bf16 v[56:59], v[32:35], v[56:59], 0
	v_cvt_f32_i32_e32 v14, v14
	v_fmac_f32_e32 v27, v10, v93
	v_lshlrev_b32_e32 v10, 1, v68
	s_waitcnt lgkmcnt(0)
	v_mfma_f32_16x16x32_bf16 v[52:55], v[36:39], v[52:55], v[56:59]
	v_mul_f32_e32 v14, v14, v67
	v_mul_f32_e32 v14, 0xbfb8aa3b, v14
	v_exp_f32_e32 v14, v14
	ds_read_b128 v[56:59], v107
	v_mfma_f32_16x16x32_bf16 v[60:63], v[32:35], v[60:63], 0
	v_add3_u32 v10, v65, v10, v103
	s_waitcnt lgkmcnt(0)
	v_mfma_f32_16x16x32_bf16 v[56:59], v[36:39], v[56:59], v[60:63]
	v_mfma_f32_16x16x32_bf16 v[70:73], v[32:35], v[70:73], 0
	s_nop 3
	ds_read_b128 v[60:63], v109
	s_waitcnt lgkmcnt(0)
	v_mfma_f32_16x16x32_bf16 v[60:63], v[36:39], v[60:63], v[70:73]
	s_nop 2
	ds_read_b128 v[70:73], v111
	v_mfma_f32_16x16x32_bf16 v[74:77], v[32:35], v[74:77], 0
	s_waitcnt lgkmcnt(0)
	v_mfma_f32_16x16x32_bf16 v[70:73], v[36:39], v[70:73], v[74:77]
	v_mfma_f32_16x16x32_bf16 v[78:81], v[32:35], v[78:81], 0
	s_nop 4
	ds_read_b128 v[74:77], v113
	s_waitcnt lgkmcnt(0)
	v_mfma_f32_16x16x32_bf16 v[74:77], v[36:39], v[74:77], v[78:81]
	s_nop 2
	ds_read_b128 v[78:81], v115
	v_mfma_f32_16x16x32_bf16 v[82:85], v[32:35], v[82:85], 0
	s_waitcnt lgkmcnt(0)
	v_mfma_f32_16x16x32_bf16 v[78:81], v[36:39], v[78:81], v[82:85]
	v_mfma_f32_16x16x32_bf16 v[32:35], v[32:35], v[86:89], 0
	s_nop 4
	ds_read_b128 v[82:85], v116
	s_waitcnt lgkmcnt(0)
	v_mfma_f32_16x16x32_bf16 v[32:35], v[36:39], v[82:85], v[32:35]
	ds_read_b128 v[36:39], v117
	s_waitcnt lgkmcnt(0)
	v_mfma_f32_16x16x32_bf16 v[36:39], v[40:43], v[36:39], v[48:51]
	s_nop 2
	ds_read_b128 v[48:51], v118
	s_waitcnt lgkmcnt(0)
	v_mfma_f32_16x16x32_bf16 v[48:51], v[40:43], v[48:51], v[52:55]
	s_nop 2
	ds_read_b128 v[52:55], v119
	s_waitcnt lgkmcnt(0)
	v_mfma_f32_16x16x32_bf16 v[52:55], v[40:43], v[52:55], v[56:59]
	s_nop 2
	ds_read_b128 v[56:59], v120
	s_waitcnt lgkmcnt(0)
	v_mfma_f32_16x16x32_bf16 v[56:59], v[40:43], v[56:59], v[60:63]
	s_nop 2
	ds_read_b128 v[60:63], v121
	s_waitcnt lgkmcnt(0)
	v_mfma_f32_16x16x32_bf16 v[60:63], v[40:43], v[60:63], v[70:73]
	s_nop 2
	ds_read_b128 v[70:73], v122
	s_waitcnt lgkmcnt(0)
	v_mfma_f32_16x16x32_bf16 v[70:73], v[40:43], v[70:73], v[74:77]
	s_nop 2
	ds_read_b128 v[74:77], v123
	s_waitcnt lgkmcnt(0)
	v_mfma_f32_16x16x32_bf16 v[74:77], v[40:43], v[74:77], v[78:81]
	s_nop 2
	ds_read_b128 v[78:81], v124
	s_waitcnt lgkmcnt(0)
	v_mfma_f32_16x16x32_bf16 v[78:81], v[40:43], v[78:81], v[32:35]
	s_nop 2
	ds_read_b128 v[32:35], v125
	ds_read_b128 v[40:43], v127
	s_waitcnt lgkmcnt(1)
	v_mfma_f32_16x16x32_bf16 v[32:35], v[44:47], v[32:35], v[36:39]
	s_nop 2
	ds_read_b128 v[36:39], v126
	s_waitcnt lgkmcnt(1)
	v_mfma_f32_16x16x32_bf16 v[40:43], v[44:47], v[40:43], v[52:55]
	s_nop 1
	v_fmac_f32_e32 v94, v14, v32
	v_add_f32_e32 v18, 0, v94
	ds_read_b128 v[52:55], v129
	s_waitcnt lgkmcnt(1)
	v_mfma_f32_16x16x32_bf16 v[36:39], v[44:47], v[36:39], v[48:51]
	s_nop 0
	v_fmac_f32_e32 v96, v14, v40
	s_nop 0
	ds_read_b128 v[48:51], v128
	s_waitcnt lgkmcnt(1)
	v_mfma_f32_16x16x32_bf16 v[52:55], v[44:47], v[52:55], v[60:63]
	s_nop 1
	v_fmac_f32_e32 v95, v14, v36
	v_add_f32_e32 v18, v18, v95
	v_add_f32_e32 v18, v18, v96
	ds_read_b128 v[60:63], v131
	s_waitcnt lgkmcnt(1)
	v_mfma_f32_16x16x32_bf16 v[48:51], v[44:47], v[48:51], v[56:59]
	v_fmac_f32_e32 v16, v14, v52
	s_nop 1
	ds_read_b128 v[56:59], v130
	s_waitcnt lgkmcnt(0)
	v_mfma_f32_16x16x32_bf16 v[56:59], v[44:47], v[56:59], v[70:73]
	s_nop 2
	ds_read_b128 v[70:73], v132
	v_fmac_f32_e32 v12, v14, v48
	v_add_f32_e32 v18, v18, v12
	v_mfma_f32_16x16x32_bf16 v[60:63], v[44:47], v[60:63], v[74:77]
	v_add_f32_e32 v18, v18, v16
	v_fmac_f32_e32 v20, v14, v56
	v_add_f32_e32 v18, v18, v20
	s_waitcnt lgkmcnt(0)
	v_mfma_f32_16x16x32_bf16 v[44:47], v[44:47], v[70:73], v[78:81]
	s_nop 2
	v_fmac_f32_e32 v24, v14, v60
	v_add_f32_e32 v18, v18, v24
	s_nop 2
	v_fmac_f32_e32 v28, v14, v44
	v_add_f32_e32 v14, v18, v28
	ds_bpermute_b32 v18, v206, v14
	s_waitcnt lgkmcnt(0)
	v_add_f32_e32 v14, v14, v18
	ds_bpermute_b32 v18, v207, v14
	s_waitcnt lgkmcnt(0)
	v_add_f32_e32 v14, v14, v18
	ds_bpermute_b32 v18, v208, v14
	s_waitcnt lgkmcnt(0)
	v_add_f32_e32 v14, v14, v18
	ds_bpermute_b32 v18, v209, v14
	s_waitcnt lgkmcnt(0)
	v_add_f32_e32 v14, v14, v18
	v_fmac_f32_e32 v95, 0xbc000000, v14
	v_fmac_f32_e32 v94, 0xbc000000, v14
	v_mul_f32_e32 v18, v95, v95
	v_fmac_f32_e32 v18, v94, v94
	v_fmac_f32_e32 v96, 0xbc000000, v14
	v_fmac_f32_e32 v18, v96, v96
	v_fmac_f32_e32 v12, 0xbc000000, v14
	v_fmac_f32_e32 v18, v12, v12
	v_fmac_f32_e32 v16, 0xbc000000, v14
	v_fmac_f32_e32 v18, v16, v16
	v_fmac_f32_e32 v20, 0xbc000000, v14
	v_fmac_f32_e32 v18, v20, v20
	v_fmac_f32_e32 v24, 0xbc000000, v14
	v_fmac_f32_e32 v18, v24, v24
	v_fmac_f32_e32 v28, 0xbc000000, v14
	v_fmac_f32_e32 v18, v28, v28
	ds_bpermute_b32 v14, v206, v18
	s_waitcnt lgkmcnt(0)
	v_add_f32_e32 v14, v18, v14
	ds_bpermute_b32 v18, v207, v14
	s_waitcnt lgkmcnt(0)
	v_add_f32_e32 v14, v14, v18
	ds_bpermute_b32 v18, v208, v14
	s_waitcnt lgkmcnt(0)
	v_add_f32_e32 v14, v14, v18
	ds_bpermute_b32 v18, v209, v14
	s_waitcnt lgkmcnt(0)
; DI void out_unit(const Inputs& in, int l, unsigned char* ws, int half, int u, LAS unsigned char* lds, int tid) {
;     ...
;     for (int r = 0; r < 4; ++r) { const int i = 16 * wave + 4 * quad + r; const float qwb = __expf((float)(128 - i) * lgb);
;         float sm = 0.f;
; #pragma unroll
;         for (int cg = 0; cg < 8; ++cg) { O[cg][r] += qwb * F[cg][r]; sm += O[cg][r]; }
;         sm += __shfl_xor(sm, 1); sm += __shfl_xor(sm, 2); sm += __shfl_xor(sm, 4); sm += __shfl_xor(sm, 8);
;         const float mean = sm * (1.f / 128.f); float vs = 0.f;
; #pragma unroll
;         for (int cg = 0; cg < 8; ++cg) { const float dd = O[cg][r] - mean; vs += dd * dd; }
;         vs += __shfl_xor(vs, 1); vs += __shfl_xor(vs, 2); vs += __shfl_xor(vs, 4); vs += __shfl_xor(vs, 8);
;         const float rinv = __builtin_amdgcn_rsqf(vs * (1.f / 128.f) + EPS);
; #pragma unroll
;         for (int cg = 0; cg < 8; ++cg) Pn[(4 * quad + r) * TS + 16 * cg + l15] = f2bf((O[cg][r] - mean) * rinv);
;     }
	v_add_f32_e32 v14, v14, v18
	v_fmamk_f32 v14, v14, 0x3c000000, v217
	v_rsq_f32_e32 v14, v14
	s_nop 0
	v_mul_f32_e32 v12, v12, v14
	v_cvt_pk_bf16_f32 v12, v12, s0
	ds_write_b16 v10, v12 offset:96
	v_mul_f32_e32 v12, v16, v14
	v_cvt_pk_bf16_f32 v12, v12, s0
	ds_write_b16 v10, v12 offset:128
	v_mul_f32_e32 v12, v20, v14
	v_cvt_pk_bf16_f32 v12, v12, s0
	ds_write_b16 v10, v12 offset:160
	v_mul_f32_e32 v12, v24, v14
	v_cvt_pk_bf16_f32 v12, v12, s0
	ds_write_b16 v10, v12 offset:192
	v_mul_f32_e32 v12, v28, v14
	v_cvt_pk_bf16_f32 v12, v12, s0
	ds_write_b16 v10, v12 offset:224
	v_sub_u32_e32 v12, 0x7f, v101
	v_cvt_f32_i32_e32 v12, v12
	v_mul_f32_e32 v18, v94, v14
	v_cvt_pk_bf16_f32 v18, v18, s0
	ds_write_b16 v10, v18
	v_mul_f32_e32 v12, v12, v67
	v_mul_f32_e32 v12, 0xbfb8aa3b, v12
	v_exp_f32_e32 v12, v12
	v_mul_f32_e32 v18, v95, v14
	v_cvt_pk_bf16_f32 v18, v18, s0
	ds_write_b16 v10, v18 offset:32
	v_fmac_f32_e32 v90, v12, v33
	v_mul_f32_e32 v18, v96, v14
	v_add_f32_e32 v14, 0, v90
	v_fmac_f32_e32 v97, v12, v37
	v_add_f32_e32 v14, v14, v97
	v_fmac_f32_e32 v98, v12, v41
	v_add_f32_e32 v14, v14, v98
	v_fmac_f32_e32 v13, v12, v49
	v_add_f32_e32 v14, v14, v13
	v_fmac_f32_e32 v17, v12, v53
	v_add_f32_e32 v14, v14, v17
	v_fmac_f32_e32 v21, v12, v57
	v_add_f32_e32 v14, v14, v21
	v_fmac_f32_e32 v25, v12, v61
	v_add_f32_e32 v14, v14, v25
	v_fmac_f32_e32 v29, v12, v45
	v_add_f32_e32 v12, v14, v29
	ds_bpermute_b32 v14, v206, v12
	v_cvt_pk_bf16_f32 v18, v18, s0
	ds_write_b16 v10, v18 offset:64
	s_waitcnt lgkmcnt(1)
	v_add_f32_e32 v12, v12, v14
	ds_bpermute_b32 v14, v207, v12
	s_waitcnt lgkmcnt(0)
	v_add_f32_e32 v12, v12, v14
	ds_bpermute_b32 v14, v208, v12
	s_waitcnt lgkmcnt(0)
	v_add_f32_e32 v12, v12, v14
	ds_bpermute_b32 v14, v209, v12
	s_waitcnt lgkmcnt(0)
	v_add_f32_e32 v12, v12, v14
	v_fmac_f32_e32 v97, 0xbc000000, v12
	v_fmac_f32_e32 v90, 0xbc000000, v12
	v_mul_f32_e32 v14, v97, v97
	v_fmac_f32_e32 v14, v90, v90
	v_fmac_f32_e32 v98, 0xbc000000, v12
	v_fmac_f32_e32 v14, v98, v98
	v_fmac_f32_e32 v13, 0xbc000000, v12
	v_fmac_f32_e32 v14, v13, v13
	v_fmac_f32_e32 v17, 0xbc000000, v12
	v_fmac_f32_e32 v14, v17, v17
	v_fmac_f32_e32 v21, 0xbc000000, v12
	v_fmac_f32_e32 v14, v21, v21
	v_fmac_f32_e32 v25, 0xbc000000, v12
	v_fmac_f32_e32 v14, v25, v25
	v_fmac_f32_e32 v29, 0xbc000000, v12
	v_fmac_f32_e32 v14, v29, v29
	ds_bpermute_b32 v12, v206, v14
	s_waitcnt lgkmcnt(0)
	v_add_f32_e32 v12, v14, v12
	ds_bpermute_b32 v14, v207, v12
	s_waitcnt lgkmcnt(0)
	v_add_f32_e32 v12, v12, v14
	ds_bpermute_b32 v14, v208, v12
	s_waitcnt lgkmcnt(0)
	v_add_f32_e32 v12, v12, v14
	ds_bpermute_b32 v14, v209, v12
	s_waitcnt lgkmcnt(0)
	v_add_f32_e32 v12, v12, v14
	v_fmamk_f32 v12, v12, 0x3c000000, v217
	v_rsq_f32_e32 v12, v12
	s_nop 0
	v_mul_f32_e32 v13, v13, v12
	v_cvt_pk_bf16_f32 v13, v13, s0
	v_mul_f32_e32 v14, v90, v12
	ds_write_b16 v10, v13 offset:368
	v_mul_f32_e32 v13, v17, v12
	v_cvt_pk_bf16_f32 v14, v14, s0
	v_cvt_pk_bf16_f32 v13, v13, s0
	ds_write_b16 v10, v14 offset:272
	v_mul_f32_e32 v14, v97, v12
	ds_write_b16 v10, v13 offset:400
	v_mul_f32_e32 v13, v21, v12
	v_cvt_pk_bf16_f32 v14, v14, s0
	v_cvt_pk_bf16_f32 v13, v13, s0
	ds_write_b16 v10, v14 offset:304
	v_mul_f32_e32 v14, v98, v12
	ds_write_b16 v10, v13 offset:432
	v_mul_f32_e32 v13, v25, v12
	v_mul_f32_e32 v12, v29, v12
	v_cvt_pk_bf16_f32 v12, v12, s0
	ds_write_b16 v10, v12 offset:496
	v_sub_u32_e32 v12, 0x80, v102
	v_cvt_f32_i32_e32 v12, v12
	v_cvt_pk_bf16_f32 v13, v13, s0
	ds_write_b16 v10, v13 offset:464
	v_cvt_pk_bf16_f32 v14, v14, s0
	v_mul_f32_e32 v12, v12, v67
	v_mul_f32_e32 v12, 0xbfb8aa3b, v12
	v_exp_f32_e32 v12, v12
	ds_write_b16 v10, v14 offset:336
	v_fmac_f32_e32 v9, v12, v34
	v_add_f32_e32 v13, 0, v9
	v_fmac_f32_e32 v8, v12, v38
	v_add_f32_e32 v13, v13, v8
	v_fmac_f32_e32 v6, v12, v42
	v_add_f32_e32 v13, v13, v6
	v_fmac_f32_e32 v5, v12, v50
	v_add_f32_e32 v13, v13, v5
	v_fmac_f32_e32 v4, v12, v54
	v_add_f32_e32 v13, v13, v4
	v_fmac_f32_e32 v2, v12, v58
	v_add_f32_e32 v13, v13, v2
	v_fmac_f32_e32 v1, v12, v62
	v_add_f32_e32 v13, v13, v1
	v_fmac_f32_e32 v0, v12, v46
	v_add_f32_e32 v12, v13, v0
	ds_bpermute_b32 v13, v206, v12
	s_waitcnt lgkmcnt(0)
	v_add_f32_e32 v12, v12, v13
	ds_bpermute_b32 v13, v207, v12
	s_waitcnt lgkmcnt(0)
	v_add_f32_e32 v12, v12, v13
	ds_bpermute_b32 v13, v208, v12
	s_waitcnt lgkmcnt(0)
	v_add_f32_e32 v12, v12, v13
	ds_bpermute_b32 v13, v209, v12
	s_waitcnt lgkmcnt(0)
	v_add_f32_e32 v12, v12, v13
	v_fmac_f32_e32 v8, 0xbc000000, v12
	v_fmac_f32_e32 v9, 0xbc000000, v12
	v_mul_f32_e32 v13, v8, v8
	v_fmac_f32_e32 v13, v9, v9
	v_fmac_f32_e32 v6, 0xbc000000, v12
	v_fmac_f32_e32 v13, v6, v6
	v_fmac_f32_e32 v5, 0xbc000000, v12
	v_fmac_f32_e32 v13, v5, v5
	v_fmac_f32_e32 v4, 0xbc000000, v12
	v_fmac_f32_e32 v13, v4, v4
	v_fmac_f32_e32 v2, 0xbc000000, v12
	v_fmac_f32_e32 v13, v2, v2
	v_fmac_f32_e32 v1, 0xbc000000, v12
	v_fmac_f32_e32 v13, v1, v1
	v_fmac_f32_e32 v0, 0xbc000000, v12
	v_fmac_f32_e32 v13, v0, v0
	ds_bpermute_b32 v12, v206, v13
	s_waitcnt lgkmcnt(0)
	v_add_f32_e32 v12, v13, v12
	ds_bpermute_b32 v13, v207, v12
	s_waitcnt lgkmcnt(0)
	v_add_f32_e32 v12, v12, v13
	ds_bpermute_b32 v13, v208, v12
	s_waitcnt lgkmcnt(0)
	v_add_f32_e32 v12, v12, v13
	ds_bpermute_b32 v13, v209, v12
	s_waitcnt lgkmcnt(0)
; #define LAS __attribute__((address_space(3)))
; DI unsigned cvt_pk_bf16(float lo, float hi) { const f32x2 v = {lo, hi}; return __builtin_bit_cast(unsigned, __builtin_convertvector(v, bf16x2_t)); }
; DI float sigmoidf_(float x) { return __builtin_amdgcn_rcpf(1.f + __builtin_amdgcn_exp2f(-1.4426950408889634f * x)); }
; #define LDS_WAIT() asm volatile("s_waitcnt lgkmcnt(0)" ::: "memory")
; DI void unpack8(const u32x4 w, float (&f)[8]) { f[0] = bflo(w.x); f[1] = bfhi(w.x); f[2] = bflo(w.y); f[3] = bfhi(w.y); f[4] = bflo(w.z); f[5] = bfhi(w.z); f[6] = bflo(w.w); f[7] = bfhi(w.w); }
; DI void out_unit(const Inputs& in, int l, unsigned char* ws, int half, int u, LAS unsigned char* lds, int tid) {
;     ...
; #pragma unroll
;         for (int cg = 0; cg < 8; ++cg) Pn[(4 * quad + r) * TS + 16 * cg + l15] = f2bf((O[cg][r] - mean) * rinv);
;     }
;     LDS_WAIT();
;     { const int rr = lane >> 2, part = lane & 3; bf16_t* rowp = proj + (size_t)(row0 + 16 * wave + rr) * PC + 128 * h + 32 * part;
;       u32x4 gv[4];
; #pragma unroll
;       for (int q = 0; q < 4; ++q) gv[q] = *(const u32x4*)(rowp + C_RG + 8 * q);
; #pragma unroll
;       for (int q = 0; q < 4; ++q) { float g[8], o[8]; unpack8(gv[q], g); unpack8(*(const LAS u32x4*)(Pn + rr * TS + 32 * part + 8 * q), o);
; #pragma unroll
;           for (int e = 0; e < 8; ++e) o[e] = g[e] * sigmoidf_(g[e]) * o[e];
;           u32x4 w; w.x = cvt_pk_bf16(o[0], o[1]); w.y = cvt_pk_bf16(o[2], o[3]); w.z = cvt_pk_bf16(o[4], o[5]); w.w = cvt_pk_bf16(o[6], o[7]);
;           *(u32x4*)(rowp + C_RQ + 8 * q) = w; } }
	v_add_f32_e32 v12, v12, v13
	v_fmamk_f32 v12, v12, 0x3c000000, v217
	v_rsq_f32_e32 v12, v12
	s_nop 0
	v_mul_f32_e32 v0, v0, v12
	v_cvt_pk_bf16_f32 v0, v0, s0
	ds_write_b16 v10, v0 offset:768
	v_sub_u32_e32 v0, 0x80, v100
	v_cvt_f32_i32_e32 v0, v0
	v_mul_f32_e32 v1, v1, v12
	v_cvt_pk_bf16_f32 v1, v1, s0
	ds_write_b16 v10, v1 offset:736
	v_mul_f32_e32 v0, v0, v67
	v_mul_f32_e32 v0, 0xbfb8aa3b, v0
	v_exp_f32_e32 v0, v0
	v_mul_f32_e32 v9, v9, v12
	v_mul_f32_e32 v8, v8, v12
	v_mul_f32_e32 v6, v6, v12
	v_fmac_f32_e32 v3, v0, v35
	v_add_f32_e32 v1, 0, v3
	v_fmac_f32_e32 v7, v0, v39
	v_add_f32_e32 v1, v1, v7
	v_fmac_f32_e32 v11, v0, v43
	v_add_f32_e32 v1, v1, v11
	v_fmac_f32_e32 v15, v0, v51
	v_add_f32_e32 v1, v1, v15
	v_fmac_f32_e32 v19, v0, v55
	v_add_f32_e32 v1, v1, v19
	v_fmac_f32_e32 v23, v0, v59
	v_add_f32_e32 v1, v1, v23
	v_fmac_f32_e32 v27, v0, v63
	v_add_f32_e32 v1, v1, v27
	v_fmac_f32_e32 v31, v0, v47
	v_add_f32_e32 v0, v1, v31
	ds_bpermute_b32 v1, v206, v0
	v_mul_f32_e32 v5, v5, v12
	v_mul_f32_e32 v4, v4, v12
	v_mul_f32_e32 v2, v2, v12
	v_cvt_pk_bf16_f32 v9, v9, s0
	s_waitcnt lgkmcnt(0)
	v_add_f32_e32 v0, v0, v1
	ds_bpermute_b32 v1, v207, v0
	v_cvt_pk_bf16_f32 v8, v8, s0
	v_cvt_pk_bf16_f32 v6, v6, s0
	v_cvt_pk_bf16_f32 v5, v5, s0
	v_cvt_pk_bf16_f32 v4, v4, s0
	s_waitcnt lgkmcnt(0)
	v_add_f32_e32 v0, v0, v1
	ds_bpermute_b32 v1, v208, v0
	v_cvt_pk_bf16_f32 v2, v2, s0
	ds_write_b16 v10, v9 offset:544
	ds_write_b16 v10, v8 offset:576
	ds_write_b16 v10, v6 offset:608
	s_waitcnt lgkmcnt(3)
	v_add_f32_e32 v0, v0, v1
	ds_bpermute_b32 v1, v209, v0
	ds_write_b16 v10, v5 offset:640
	ds_write_b16 v10, v4 offset:672
	ds_write_b16 v10, v2 offset:704
	v_lshlrev_b32_e32 v2, 6, v66
	s_waitcnt lgkmcnt(3)
	v_add_f32_e32 v0, v0, v1
	v_fmac_f32_e32 v7, 0xbc000000, v0
	v_fmac_f32_e32 v3, 0xbc000000, v0
	v_mul_f32_e32 v1, v7, v7
	v_fmac_f32_e32 v1, v3, v3
	v_fmac_f32_e32 v11, 0xbc000000, v0
	v_fmac_f32_e32 v1, v11, v11
	v_fmac_f32_e32 v15, 0xbc000000, v0
	v_fmac_f32_e32 v1, v15, v15
	v_fmac_f32_e32 v19, 0xbc000000, v0
	v_fmac_f32_e32 v1, v19, v19
	v_fmac_f32_e32 v23, 0xbc000000, v0
	v_fmac_f32_e32 v1, v23, v23
	v_fmac_f32_e32 v27, 0xbc000000, v0
	v_fmac_f32_e32 v1, v27, v27
	v_fmac_f32_e32 v31, 0xbc000000, v0
	v_fmac_f32_e32 v1, v31, v31
	ds_bpermute_b32 v0, v206, v1
	v_and_b32_e32 v176, 0xc0, v2
	s_waitcnt lgkmcnt(0)
	v_add_f32_e32 v0, v1, v0
	ds_bpermute_b32 v1, v207, v0
	s_waitcnt lgkmcnt(0)
	v_add_f32_e32 v0, v0, v1
	ds_bpermute_b32 v1, v208, v0
	s_waitcnt lgkmcnt(0)
	v_add_f32_e32 v0, v0, v1
	ds_bpermute_b32 v1, v209, v0
	s_waitcnt lgkmcnt(0)
	v_add_f32_e32 v0, v0, v1
	v_fmamk_f32 v0, v0, 0x3c000000, v217
	v_rsq_f32_e32 v0, v0
	s_nop 0
	v_mul_f32_e32 v1, v3, v0
	v_cvt_pk_bf16_f32 v1, v1, s0
	ds_write_b16 v10, v1 offset:816
	v_mul_f32_e32 v1, v7, v0
	v_cvt_pk_bf16_f32 v1, v1, s0
	ds_write_b16 v10, v1 offset:848
	v_mul_f32_e32 v1, v11, v0
	v_cvt_pk_bf16_f32 v1, v1, s0
	ds_write_b16 v10, v1 offset:880
	v_mul_f32_e32 v1, v15, v0
	v_cvt_pk_bf16_f32 v1, v1, s0
	ds_write_b16 v10, v1 offset:912
	v_mul_f32_e32 v1, v19, v0
	v_cvt_pk_bf16_f32 v1, v1, s0
	ds_write_b16 v10, v1 offset:944
	v_mul_f32_e32 v1, v23, v0
	v_cvt_pk_bf16_f32 v1, v1, s0
	ds_write_b16 v10, v1 offset:976
	v_mul_f32_e32 v1, v27, v0
	v_mul_f32_e32 v0, v31, v0
	v_cvt_pk_bf16_f32 v1, v1, s0
	v_cvt_pk_bf16_f32 v0, v0, s0
	ds_write_b16 v10, v1 offset:1008
	ds_write_b16 v10, v0 offset:1040
	v_bfe_u32 v10, v66, 2, 4
	v_add_u32_e32 v0, s14, v69
	v_or_b32_e32 v0, v0, v10
	v_ashrrev_i32_e32 v1, 31, v0
	v_lshlrev_b64 v[0:1], 14, v[0:1]
	v_lshl_add_u64 v[0:1], s[6:7], 0, v[0:1]
	v_lshl_add_u64 v[0:1], v[0:1], 0, s[44:45]
	v_lshl_add_u64 v[8:9], v[0:1], 0, v[176:177]
	s_mov_b64 s[14:15], 0x1800
	v_add_co_u32_e32 v0, vcc, s30, v8
	s_waitcnt lgkmcnt(0)
	v_lshl_add_u64 v[16:17], v[8:9], 0, s[14:15]
	s_nop 0
	v_addc_co_u32_e32 v1, vcc, 0, v9, vcc
	global_load_dwordx4 v[12:15], v[0:1], off offset:2048
	s_nop 0
	global_load_dwordx4 v[0:3], v[16:17], off offset:48
	global_load_dwordx4 v[4:7], v[16:17], off offset:32
	s_nop 0
	global_load_dwordx4 v[16:19], v[16:17], off offset:16
	v_mul_u32_u24_e32 v10, 0x110, v10
	v_add3_u32 v10, v65, v10, v176
	ds_read_b128 v[20:23], v10
	ds_read_b128 v[24:27], v10 offset:16
	ds_read_b128 v[28:31], v10 offset:32
	ds_read_b128 v[32:35], v10 offset:48
	s_waitcnt lgkmcnt(3)
	v_lshlrev_b32_e32 v36, 16, v20
	v_and_b32_e32 v37, 0xffff0000, v20
	v_lshlrev_b32_e32 v20, 16, v21
	v_and_b32_e32 v21, 0xffff0000, v21
	s_waitcnt vmcnt(3)
	v_lshlrev_b32_e32 v10, 16, v12
	v_and_b32_e32 v11, 0xffff0000, v12
	v_mul_f32_e32 v12, 0xbfb8aa3b, v10
	v_exp_f32_e32 v12, v12
	s_nop 0
	v_add_f32_e32 v12, 1.0, v12
	v_rcp_f32_e32 v38, v12
	v_mul_f32_e32 v12, 0xbfb8aa3b, v11
	v_exp_f32_e32 v12, v12
	s_nop 0
	v_add_f32_e32 v12, 1.0, v12
	v_rcp_f32_e32 v39, v12
	v_lshlrev_b32_e32 v12, 16, v13
	v_and_b32_e32 v13, 0xffff0000, v13
	v_pk_mul_f32 v[10:11], v[38:39], v[10:11]
	s_nop 0
	v_pk_mul_f32 v[10:11], v[10:11], v[36:37]
	v_mul_f32_e32 v36, 0xbfb8aa3b, v12
	v_mul_f32_e32 v37, 0xbfb8aa3b, v13
	v_exp_f32_e32 v36, v36
	v_exp_f32_e32 v37, v37
	v_cvt_pk_bf16_f32 v10, v10, v11
	v_add_f32_e32 v36, 1.0, v36
	v_add_f32_e32 v37, 1.0, v37
	v_rcp_f32_e32 v36, v36
	v_rcp_f32_e32 v37, v37
	s_nop 0
	v_pk_mul_f32 v[12:13], v[36:37], v[12:13]
	s_nop 0
	v_pk_mul_f32 v[12:13], v[12:13], v[20:21]
	v_lshlrev_b32_e32 v20, 16, v14
	v_and_b32_e32 v21, 0xffff0000, v14
	v_mul_f32_e32 v14, 0xbfb8aa3b, v20
	v_exp_f32_e32 v14, v14
	v_lshlrev_b32_e32 v36, 16, v22
	v_and_b32_e32 v37, 0xffff0000, v22
	v_lshlrev_b32_e32 v22, 16, v23
	v_add_f32_e32 v14, 1.0, v14
	v_rcp_f32_e32 v38, v14
	v_mul_f32_e32 v14, 0xbfb8aa3b, v21
	v_exp_f32_e32 v14, v14
	v_and_b32_e32 v23, 0xffff0000, v23
	v_cvt_pk_bf16_f32 v11, v12, v13
	v_add_f32_e32 v14, 1.0, v14
	v_rcp_f32_e32 v39, v14
	v_lshlrev_b32_e32 v14, 16, v15
	v_and_b32_e32 v15, 0xffff0000, v15
	v_pk_mul_f32 v[20:21], v[38:39], v[20:21]
	s_nop 0
	v_pk_mul_f32 v[20:21], v[20:21], v[36:37]
	v_mul_f32_e32 v36, 0xbfb8aa3b, v14
	v_mul_f32_e32 v37, 0xbfb8aa3b, v15
	v_exp_f32_e32 v36, v36
	v_exp_f32_e32 v37, v37
	v_cvt_pk_bf16_f32 v12, v20, v21
	v_add_f32_e32 v36, 1.0, v36
	v_add_f32_e32 v37, 1.0, v37
	v_rcp_f32_e32 v36, v36
	v_rcp_f32_e32 v37, v37
	s_nop 0
	v_pk_mul_f32 v[14:15], v[36:37], v[14:15]
	s_nop 0
	v_pk_mul_f32 v[14:15], v[14:15], v[22:23]
	s_nop 0
	v_cvt_pk_bf16_f32 v13, v14, v15
	global_store_dwordx4 v[8:9], v[10:13], off offset:3072
	s_waitcnt vmcnt(1)
; #define LAS __attribute__((address_space(3)))
; DI unsigned cvt_pk_bf16(float lo, float hi) { const f32x2 v = {lo, hi}; return __builtin_bit_cast(unsigned, __builtin_convertvector(v, bf16x2_t)); }
; DI float sigmoidf_(float x) { return __builtin_amdgcn_rcpf(1.f + __builtin_amdgcn_exp2f(-1.4426950408889634f * x)); }
; DI void unpack8(const u32x4 w, float (&f)[8]) { f[0] = bflo(w.x); f[1] = bfhi(w.x); f[2] = bflo(w.y); f[3] = bfhi(w.y); f[4] = bflo(w.z); f[5] = bfhi(w.z); f[6] = bflo(w.w); f[7] = bfhi(w.w); }
; DI void out_unit(const Inputs& in, int l, unsigned char* ws, int half, int u, LAS unsigned char* lds, int tid) {
;     ...
;       for (int q = 0; q < 4; ++q) gv[q] = *(const u32x4*)(rowp + C_RG + 8 * q);
; #pragma unroll
;       for (int q = 0; q < 4; ++q) { float g[8], o[8]; unpack8(gv[q], g); unpack8(*(const LAS u32x4*)(Pn + rr * TS + 32 * part + 8 * q), o);
; #pragma unroll
;           for (int e = 0; e < 8; ++e) o[e] = g[e] * sigmoidf_(g[e]) * o[e];
;           u32x4 w; w.x = cvt_pk_bf16(o[0], o[1]); w.y = cvt_pk_bf16(o[2], o[3]); w.z = cvt_pk_bf16(o[4], o[5]); w.w = cvt_pk_bf16(o[6], o[7]);
;           *(u32x4*)(rowp + C_RQ + 8 * q) = w; } }
;     __syncthreads();
	s_nop 0
	v_lshlrev_b32_e32 v10, 16, v16
	v_and_b32_e32 v11, 0xffff0000, v16
	v_mul_f32_e32 v14, 0xbfb8aa3b, v10
	v_mul_f32_e32 v15, 0xbfb8aa3b, v11
	v_exp_f32_e32 v14, v14
	v_exp_f32_e32 v15, v15
	s_waitcnt lgkmcnt(2)
	v_lshlrev_b32_e32 v12, 16, v24
	v_and_b32_e32 v13, 0xffff0000, v24
	v_add_f32_e32 v14, 1.0, v14
	v_add_f32_e32 v15, 1.0, v15
	v_rcp_f32_e32 v14, v14
	v_rcp_f32_e32 v15, v15
	s_nop 0
	v_pk_mul_f32 v[10:11], v[14:15], v[10:11]
	s_nop 0
	v_pk_mul_f32 v[10:11], v[10:11], v[12:13]
	v_lshlrev_b32_e32 v12, 16, v17
	v_and_b32_e32 v13, 0xffff0000, v17
	v_mul_f32_e32 v16, 0xbfb8aa3b, v12
	v_mul_f32_e32 v17, 0xbfb8aa3b, v13
	v_exp_f32_e32 v16, v16
	v_exp_f32_e32 v17, v17
	v_lshlrev_b32_e32 v14, 16, v25
	v_and_b32_e32 v15, 0xffff0000, v25
	v_add_f32_e32 v16, 1.0, v16
	v_add_f32_e32 v17, 1.0, v17
	v_rcp_f32_e32 v16, v16
	v_rcp_f32_e32 v17, v17
	v_cvt_pk_bf16_f32 v10, v10, v11
	v_pk_mul_f32 v[12:13], v[16:17], v[12:13]
	s_nop 0
	v_pk_mul_f32 v[12:13], v[12:13], v[14:15]
	v_lshlrev_b32_e32 v14, 16, v18
	v_and_b32_e32 v15, 0xffff0000, v18
	v_mul_f32_e32 v18, 0xbfb8aa3b, v14
	v_exp_f32_e32 v18, v18
	v_lshlrev_b32_e32 v16, 16, v26
	v_and_b32_e32 v17, 0xffff0000, v26
	v_cvt_pk_bf16_f32 v11, v12, v13
	v_add_f32_e32 v18, 1.0, v18
	v_rcp_f32_e32 v20, v18
	v_mul_f32_e32 v18, 0xbfb8aa3b, v15
	v_exp_f32_e32 v18, v18
	s_nop 0
	v_add_f32_e32 v18, 1.0, v18
	v_rcp_f32_e32 v21, v18
	v_lshlrev_b32_e32 v18, 16, v27
	v_pk_mul_f32 v[14:15], v[20:21], v[14:15]
	s_nop 0
	v_pk_mul_f32 v[14:15], v[14:15], v[16:17]
	v_lshlrev_b32_e32 v16, 16, v19
	v_and_b32_e32 v17, 0xffff0000, v19
	v_mul_f32_e32 v20, 0xbfb8aa3b, v16
	v_mul_f32_e32 v21, 0xbfb8aa3b, v17
	v_exp_f32_e32 v20, v20
	v_exp_f32_e32 v21, v21
	v_and_b32_e32 v19, 0xffff0000, v27
	v_cvt_pk_bf16_f32 v12, v14, v15
	v_add_f32_e32 v20, 1.0, v20
	v_add_f32_e32 v21, 1.0, v21
	v_rcp_f32_e32 v20, v20
	v_rcp_f32_e32 v21, v21
	s_nop 0
	v_pk_mul_f32 v[16:17], v[20:21], v[16:17]
	s_nop 0
	v_pk_mul_f32 v[16:17], v[16:17], v[18:19]
	s_nop 0
	v_cvt_pk_bf16_f32 v13, v16, v17
	global_store_dwordx4 v[8:9], v[10:13], off offset:3088
	s_nop 1
	v_lshlrev_b32_e32 v10, 16, v4
	v_and_b32_e32 v11, 0xffff0000, v4
	v_mul_f32_e32 v4, 0xbfb8aa3b, v10
	v_exp_f32_e32 v4, v4
	s_waitcnt lgkmcnt(1)
	v_lshlrev_b32_e32 v12, 16, v28
	v_and_b32_e32 v13, 0xffff0000, v28
	v_add_f32_e32 v4, 1.0, v4
	v_rcp_f32_e32 v14, v4
	v_mul_f32_e32 v4, 0xbfb8aa3b, v11
	v_exp_f32_e32 v4, v4
	s_nop 0
	v_add_f32_e32 v4, 1.0, v4
	v_rcp_f32_e32 v15, v4
	v_lshlrev_b32_e32 v4, 16, v5
	v_and_b32_e32 v5, 0xffff0000, v5
	v_pk_mul_f32 v[10:11], v[14:15], v[10:11]
	v_mul_f32_e32 v14, 0xbfb8aa3b, v4
	v_mul_f32_e32 v15, 0xbfb8aa3b, v5
	v_exp_f32_e32 v14, v14
	v_exp_f32_e32 v15, v15
	v_pk_mul_f32 v[10:11], v[10:11], v[12:13]
	v_lshlrev_b32_e32 v12, 16, v29
	v_add_f32_e32 v14, 1.0, v14
	v_add_f32_e32 v15, 1.0, v15
	v_rcp_f32_e32 v14, v14
	v_rcp_f32_e32 v15, v15
	v_and_b32_e32 v13, 0xffff0000, v29
	v_pk_mul_f32 v[4:5], v[14:15], v[4:5]
	s_nop 0
	v_pk_mul_f32 v[12:13], v[4:5], v[12:13]
	v_lshlrev_b32_e32 v4, 16, v6
	v_and_b32_e32 v5, 0xffff0000, v6
	v_mul_f32_e32 v6, 0xbfb8aa3b, v4
	v_exp_f32_e32 v6, v6
	v_lshlrev_b32_e32 v14, 16, v30
	v_and_b32_e32 v15, 0xffff0000, v30
	v_add_f32_e32 v6, 1.0, v6
	v_rcp_f32_e32 v16, v6
	v_mul_f32_e32 v6, 0xbfb8aa3b, v5
	v_exp_f32_e32 v6, v6
	s_nop 0
	v_add_f32_e32 v6, 1.0, v6
	v_rcp_f32_e32 v17, v6
	v_lshlrev_b32_e32 v6, 16, v31
	v_pk_mul_f32 v[4:5], v[16:17], v[4:5]
	s_nop 0
	v_pk_mul_f32 v[14:15], v[4:5], v[14:15]
	v_lshlrev_b32_e32 v4, 16, v7
	v_and_b32_e32 v5, 0xffff0000, v7
	v_mul_f32_e32 v16, 0xbfb8aa3b, v4
	v_mul_f32_e32 v17, 0xbfb8aa3b, v5
	v_exp_f32_e32 v16, v16
	v_exp_f32_e32 v17, v17
	v_and_b32_e32 v7, 0xffff0000, v31
	v_add_f32_e32 v16, 1.0, v16
	v_add_f32_e32 v17, 1.0, v17
	v_rcp_f32_e32 v16, v16
	v_rcp_f32_e32 v17, v17
	s_nop 0
	v_pk_mul_f32 v[4:5], v[16:17], v[4:5]
	s_nop 0
	v_pk_mul_f32 v[16:17], v[4:5], v[6:7]
	v_cvt_pk_bf16_f32 v4, v10, v11
	v_cvt_pk_bf16_f32 v5, v12, v13
	v_cvt_pk_bf16_f32 v6, v14, v15
	v_cvt_pk_bf16_f32 v7, v16, v17
	global_store_dwordx4 v[8:9], v[4:7], off offset:3104
	s_nop 1
	v_lshlrev_b32_e32 v4, 16, v0
	v_and_b32_e32 v5, 0xffff0000, v0
	v_mul_f32_e32 v0, 0xbfb8aa3b, v4
	v_exp_f32_e32 v0, v0
	s_waitcnt lgkmcnt(0)
	v_lshlrev_b32_e32 v6, 16, v32
	v_and_b32_e32 v7, 0xffff0000, v32
	v_add_f32_e32 v0, 1.0, v0
	v_rcp_f32_e32 v10, v0
	v_mul_f32_e32 v0, 0xbfb8aa3b, v5
	v_exp_f32_e32 v0, v0
	s_nop 0
	v_add_f32_e32 v0, 1.0, v0
	v_rcp_f32_e32 v11, v0
	v_lshlrev_b32_e32 v0, 16, v1
	v_and_b32_e32 v1, 0xffff0000, v1
	v_pk_mul_f32 v[4:5], v[10:11], v[4:5]
	v_mul_f32_e32 v10, 0xbfb8aa3b, v0
	v_mul_f32_e32 v11, 0xbfb8aa3b, v1
	v_exp_f32_e32 v10, v10
	v_exp_f32_e32 v11, v11
	v_pk_mul_f32 v[4:5], v[4:5], v[6:7]
	v_lshlrev_b32_e32 v6, 16, v33
	v_add_f32_e32 v10, 1.0, v10
	v_add_f32_e32 v11, 1.0, v11
	v_rcp_f32_e32 v10, v10
	v_rcp_f32_e32 v11, v11
	v_and_b32_e32 v7, 0xffff0000, v33
	v_pk_mul_f32 v[0:1], v[10:11], v[0:1]
	s_nop 0
	v_pk_mul_f32 v[6:7], v[0:1], v[6:7]
	v_lshlrev_b32_e32 v0, 16, v2
	v_and_b32_e32 v1, 0xffff0000, v2
	v_mul_f32_e32 v2, 0xbfb8aa3b, v0
	v_exp_f32_e32 v2, v2
	v_lshlrev_b32_e32 v10, 16, v34
	v_and_b32_e32 v11, 0xffff0000, v34
	v_add_f32_e32 v2, 1.0, v2
	v_rcp_f32_e32 v12, v2
	v_mul_f32_e32 v2, 0xbfb8aa3b, v1
	v_exp_f32_e32 v2, v2
	s_nop 0
	v_add_f32_e32 v2, 1.0, v2
	v_rcp_f32_e32 v13, v2
	v_lshlrev_b32_e32 v2, 16, v35
	v_pk_mul_f32 v[0:1], v[12:13], v[0:1]
	s_nop 0
	v_pk_mul_f32 v[10:11], v[0:1], v[10:11]
	v_lshlrev_b32_e32 v0, 16, v3
	v_and_b32_e32 v1, 0xffff0000, v3
	v_mul_f32_e32 v12, 0xbfb8aa3b, v0
	v_mul_f32_e32 v13, 0xbfb8aa3b, v1
	v_exp_f32_e32 v12, v12
	v_exp_f32_e32 v13, v13
	v_and_b32_e32 v3, 0xffff0000, v35
	v_add_f32_e32 v12, 1.0, v12
	v_add_f32_e32 v13, 1.0, v13
	v_rcp_f32_e32 v12, v12
	v_rcp_f32_e32 v13, v13
	s_nop 0
	v_pk_mul_f32 v[0:1], v[12:13], v[0:1]
	s_nop 0
	v_pk_mul_f32 v[12:13], v[0:1], v[2:3]
	v_cvt_pk_bf16_f32 v0, v4, v5
	v_cvt_pk_bf16_f32 v1, v6, v7
	v_cvt_pk_bf16_f32 v2, v10, v11
	v_cvt_pk_bf16_f32 v3, v12, v13
	global_store_dwordx4 v[8:9], v[0:3], off offset:3120
	s_barrier
	s_cbranch_scc0 .LBB0_731
